# v3 plus: out-proj and layer-0 down-proj fused epilogues store 16 B per lane (pairs of 8-byte bf16 stores merged through v_permlane32_swap + v_permlane16_swap): 32 -> 16 store instructions per lane
# speedup vs baseline: 1.0172x; 1.0172x over previous
.LBB0_258:
	s_or_b64 exec, exec, s[0:1]
	s_waitcnt vmcnt(0) lgkmcnt(0)
	s_barrier
	v_mov_b32_e32 v210, 0
	ds_read_b32 v211, v210 offset:10240
	v_lshl_add_u32 v210, v225, 2, 0
	s_waitcnt lgkmcnt(0)
	ds_read_b32 v212, v210 offset:8192
	v_add_u32_e32 v220, s30, v225
	s_add_u32 s0, s16, 0x3000000
	s_waitcnt vmcnt(20)
	v_or_b32_e32 v211, v211, v224
	v_ashrrev_i32_e32 v221, 31, v220
	s_waitcnt lgkmcnt(0)
	v_pk_mul_f32 v[138:139], v[138:139], v[212:213] op_sel_hi:[1,0]
	v_pk_mul_f32 v[140:141], v[140:141], v[212:213] op_sel_hi:[1,0]
	s_waitcnt vmcnt(3)
	v_pk_fma_f32 v[206:207], v[142:143], v[138:139], v[206:207]
	v_mov_b32_e32 v138, 0x7fc00000
	v_cmp_ne_u32_e32 vcc, 0, v211
	s_addc_u32 s1, s17, 0
	v_pk_fma_f32 v[140:141], v[144:145], v[140:141], v[208:209]
	v_cndmask_b32_e32 v209, v206, v138, vcc
	v_cndmask_b32_e32 v211, v207, v138, vcc
	v_lshlrev_b64 v[206:207], 11, v[220:221]
	v_lshl_add_u64 v[206:207], s[0:1], 0, v[206:207]
	v_cndmask_b32_e32 v139, v140, v138, vcc
	v_cndmask_b32_e32 v208, v141, v138, vcc
	v_cvt_pk_bf16_f32 v140, v209, v211
	v_cvt_pk_bf16_f32 v141, v139, v208
	v_lshl_add_u64 v[206:207], v[214:215], 1, v[206:207]
	v_pk_mul_f32 v[126:127], v[126:127], v[212:213] op_sel_hi:[1,0]
	v_mbcnt_lo_u32_b32 v238, -1, 0
	v_mbcnt_hi_u32_b32 v238, -1, v238
	v_lshrrev_b32_e32 v238, 4, v238
	v_lshlrev_b32_e32 v238, 3, v238
	v_mov_b32_e32 v239, 0
	v_mov_b32_e32 v240, v140
	v_mov_b32_e32 v241, v141
	v_mul_f32_e32 v140, v211, v211
	v_mul_f32_e32 v141, v208, v208
	v_pk_mul_f32 v[128:129], v[128:129], v[212:213] op_sel_hi:[1,0]
	s_waitcnt vmcnt(3)
	v_pk_fma_f32 v[126:127], v[134:135], v[126:127], v[202:203]
	v_fmac_f32_e32 v140, v209, v209
	v_fmac_f32_e32 v141, v139, v139
	v_pk_fma_f32 v[128:129], v[136:137], v[128:129], v[204:205]
	v_cndmask_b32_e32 v127, v127, v138, vcc
	v_add_f32_e32 v139, v140, v141
	v_cndmask_b32_e32 v129, v129, v138, vcc
	v_cndmask_b32_e32 v140, v126, v138, vcc
	v_cvt_pk_bf16_f32 v126, v140, v127
	v_mul_f32_e32 v127, v127, v127
	v_cndmask_b32_e32 v128, v128, v138, vcc
	v_fmac_f32_e32 v127, v140, v140
	v_mul_f32_e32 v140, v129, v129
	v_pk_mul_f32 v[120:121], v[120:121], v[212:213] op_sel_hi:[1,0]
	v_pk_mul_f32 v[118:119], v[118:119], v[212:213] op_sel_hi:[1,0]
	v_fmac_f32_e32 v140, v128, v128
	s_waitcnt vmcnt(2)
	v_pk_fma_f32 v[118:119], v[130:131], v[118:119], v[198:199]
	v_pk_fma_f32 v[120:121], v[132:133], v[120:121], v[200:201]
	v_add_f32_e32 v127, v127, v140
	v_cndmask_b32_e32 v121, v121, v138, vcc
	v_cndmask_b32_e32 v119, v119, v138, vcc
	v_add_f32_e32 v127, v139, v127
	v_cndmask_b32_e32 v120, v120, v138, vcc
	v_cndmask_b32_e32 v118, v118, v138, vcc
	v_mul_f32_e32 v139, v119, v119
	v_mul_f32_e32 v140, v121, v121
	v_pk_mul_f32 v[116:117], v[116:117], v[212:213] op_sel_hi:[1,0]
	v_pk_mul_f32 v[114:115], v[114:115], v[212:213] op_sel_hi:[1,0]
	v_fmac_f32_e32 v139, v118, v118
	v_fmac_f32_e32 v140, v120, v120
	s_waitcnt vmcnt(1)
	v_pk_fma_f32 v[114:115], v[122:123], v[114:115], v[194:195]
	v_pk_fma_f32 v[116:117], v[124:125], v[116:117], v[196:197]
	v_add_f32_e32 v139, v139, v140
	v_cndmask_b32_e32 v140, v117, v138, vcc
	v_cndmask_b32_e32 v194, v115, v138, vcc
	v_add_f32_e32 v127, v139, v127
	v_cndmask_b32_e32 v139, v116, v138, vcc
	v_cndmask_b32_e32 v141, v114, v138, vcc
	v_mul_f32_e32 v114, v194, v194
	v_mul_f32_e32 v115, v140, v140
	v_fmac_f32_e32 v114, v141, v141
	v_fmac_f32_e32 v115, v139, v139
	v_add_f32_e32 v114, v114, v115
	v_add_f32_e32 v114, v114, v127
	ds_bpermute_b32 v115, v1, v114
	v_cvt_pk_bf16_f32 v127, v128, v129
	v_mov_b32_e32 v242, v126
	v_mov_b32_e32 v243, v127
	s_nop 1
	v_permlane32_swap_b32_e32 v240, v242
	v_permlane32_swap_b32_e32 v241, v243
	s_nop 0
	v_permlane16_swap_b32_e32 v240, v242
	v_permlane16_swap_b32_e32 v241, v243
	v_lshl_add_u64 v[236:237], v[206:207], 0, v[238:239]
	global_store_dwordx4 v[236:237], v[240:243], off
	v_cvt_pk_bf16_f32 v116, v118, v119
	v_cvt_pk_bf16_f32 v117, v120, v121
	s_waitcnt lgkmcnt(0)
	v_add_f32_e32 v114, v114, v115
	ds_bpermute_b32 v115, v233, v114
	v_mov_b32_e32 v244, v116
	v_mov_b32_e32 v245, v117
	v_cvt_pk_bf16_f32 v116, v141, v194
	v_cvt_pk_bf16_f32 v117, v139, v140
	v_mov_b32_e32 v246, v116
	v_mov_b32_e32 v247, v117
	s_nop 1
	v_permlane32_swap_b32_e32 v244, v246
	v_permlane32_swap_b32_e32 v245, v247
	s_nop 0
	v_permlane16_swap_b32_e32 v244, v246
	v_permlane16_swap_b32_e32 v245, v247
	v_lshl_add_u64 v[236:237], v[206:207], 0, v[238:239]
	global_store_dwordx4 v[236:237], v[244:247], off offset:256
	s_and_saveexec_b64 s[2:3], s[4:5]
	s_cbranch_execz .LBB0_260
	v_lshl_add_u32 v116, v225, 4, s31
	s_waitcnt lgkmcnt(0)
	v_add_f32_e32 v114, v114, v115
	ds_write_b32 v116, v114 offset:16384
.LBB0_260:
	s_or_b64 exec, exec, s[2:3]
	ds_read_b32 v116, v210 offset:8256
	v_or_b32_e32 v114, 16, v225
	v_add_u32_e32 v118, s30, v114
	v_ashrrev_i32_e32 v119, 31, v118
	s_waitcnt lgkmcnt(0)
	v_pk_mul_f32 v[112:113], v[112:113], v[116:117] op_sel_hi:[1,0]
	s_nop 0
	v_pk_fma_f32 v[112:113], v[144:145], v[112:113], v[192:193]
	v_pk_mul_f32 v[110:111], v[110:111], v[116:117] op_sel_hi:[1,0]
	v_cndmask_b32_e32 v115, v112, v138, vcc
	v_cndmask_b32_e32 v117, v113, v138, vcc
	v_lshlrev_b64 v[112:113], 11, v[118:119]
	v_pk_fma_f32 v[110:111], v[142:143], v[110:111], v[190:191]
	v_lshl_add_u64 v[112:113], s[0:1], 0, v[112:113]
	v_cndmask_b32_e32 v120, v110, v138, vcc
	v_cndmask_b32_e32 v121, v111, v138, vcc
	v_cvt_pk_bf16_f32 v110, v120, v121
	v_cvt_pk_bf16_f32 v111, v115, v117
	v_lshl_add_u64 v[112:113], v[214:215], 1, v[112:113]
	v_pk_mul_f32 v[106:107], v[106:107], v[116:117] op_sel_hi:[1,0]
	v_mov_b32_e32 v240, v110
	v_mov_b32_e32 v241, v111
	v_mul_f32_e32 v110, v121, v121
	v_mul_f32_e32 v111, v117, v117
	v_pk_mul_f32 v[108:109], v[108:109], v[116:117] op_sel_hi:[1,0]
	v_pk_fma_f32 v[106:107], v[134:135], v[106:107], v[186:187]
	v_fmac_f32_e32 v110, v120, v120
	v_fmac_f32_e32 v111, v115, v115
	v_pk_fma_f32 v[108:109], v[136:137], v[108:109], v[188:189]
	v_cndmask_b32_e32 v107, v107, v138, vcc
	v_add_f32_e32 v110, v110, v111
	v_cndmask_b32_e32 v109, v109, v138, vcc
	v_cndmask_b32_e32 v111, v106, v138, vcc
	v_cvt_pk_bf16_f32 v106, v111, v107
	v_mul_f32_e32 v107, v107, v107
	v_cndmask_b32_e32 v108, v108, v138, vcc
	v_fmac_f32_e32 v107, v111, v111
	v_mul_f32_e32 v111, v109, v109
	v_pk_mul_f32 v[104:105], v[104:105], v[116:117] op_sel_hi:[1,0]
	v_pk_mul_f32 v[102:103], v[102:103], v[116:117] op_sel_hi:[1,0]
	v_fmac_f32_e32 v111, v108, v108
	v_pk_fma_f32 v[104:105], v[132:133], v[104:105], v[184:185]
	v_pk_fma_f32 v[102:103], v[130:131], v[102:103], v[182:183]
	v_add_f32_e32 v107, v107, v111
	v_cndmask_b32_e32 v105, v105, v138, vcc
	v_cndmask_b32_e32 v103, v103, v138, vcc
	v_add_f32_e32 v107, v110, v107
	v_cndmask_b32_e32 v104, v104, v138, vcc
	v_cndmask_b32_e32 v102, v102, v138, vcc
	v_mul_f32_e32 v110, v103, v103
	v_mul_f32_e32 v111, v105, v105
	v_pk_mul_f32 v[100:101], v[100:101], v[116:117] op_sel_hi:[1,0]
	v_pk_mul_f32 v[98:99], v[98:99], v[116:117] op_sel_hi:[1,0]
	v_fmac_f32_e32 v110, v102, v102
	v_fmac_f32_e32 v111, v104, v104
	v_pk_fma_f32 v[100:101], v[124:125], v[100:101], v[180:181]
	v_pk_fma_f32 v[98:99], v[122:123], v[98:99], v[178:179]
	v_add_f32_e32 v110, v110, v111
	v_cndmask_b32_e32 v111, v101, v138, vcc
	v_cndmask_b32_e32 v116, v99, v138, vcc
	v_add_f32_e32 v107, v110, v107
	v_cndmask_b32_e32 v110, v100, v138, vcc
	v_cndmask_b32_e32 v115, v98, v138, vcc
	v_mul_f32_e32 v98, v116, v116
	v_mul_f32_e32 v99, v111, v111
	v_fmac_f32_e32 v98, v115, v115
	v_fmac_f32_e32 v99, v110, v110
	v_add_f32_e32 v98, v98, v99
	v_add_f32_e32 v98, v98, v107
	ds_bpermute_b32 v99, v1, v98
	v_cvt_pk_bf16_f32 v107, v108, v109
	v_mov_b32_e32 v242, v106
	v_mov_b32_e32 v243, v107
	s_nop 1
	v_permlane32_swap_b32_e32 v240, v242
	v_permlane32_swap_b32_e32 v241, v243
	s_nop 0
	v_permlane16_swap_b32_e32 v240, v242
	v_permlane16_swap_b32_e32 v241, v243
	v_lshl_add_u64 v[236:237], v[112:113], 0, v[238:239]
	global_store_dwordx4 v[236:237], v[240:243], off
	v_cvt_pk_bf16_f32 v100, v102, v103
	v_cvt_pk_bf16_f32 v101, v104, v105
	s_waitcnt lgkmcnt(0)
	v_add_f32_e32 v98, v98, v99
	ds_bpermute_b32 v99, v233, v98
	v_mov_b32_e32 v244, v100
	v_mov_b32_e32 v245, v101
	v_cvt_pk_bf16_f32 v100, v115, v116
	v_cvt_pk_bf16_f32 v101, v110, v111
	v_mov_b32_e32 v246, v100
	v_mov_b32_e32 v247, v101
	s_nop 1
	v_permlane32_swap_b32_e32 v244, v246
	v_permlane32_swap_b32_e32 v245, v247
	s_nop 0
	v_permlane16_swap_b32_e32 v244, v246
	v_permlane16_swap_b32_e32 v245, v247
	v_lshl_add_u64 v[236:237], v[112:113], 0, v[238:239]
	global_store_dwordx4 v[236:237], v[244:247], off offset:256
	s_and_saveexec_b64 s[2:3], s[4:5]
	s_cbranch_execz .LBB0_262
	v_lshl_add_u32 v100, v114, 4, s31
	s_waitcnt lgkmcnt(0)
	v_add_f32_e32 v98, v98, v99
	ds_write_b32 v100, v98 offset:16384
.LBB0_262:
	s_or_b64 exec, exec, s[2:3]
	ds_read_b32 v100, v210 offset:8320
	v_or_b32_e32 v98, 32, v225
	v_add_u32_e32 v102, s30, v98
	v_ashrrev_i32_e32 v103, 31, v102
	v_lshlrev_b64 v[102:103], 11, v[102:103]
	s_waitcnt lgkmcnt(0)
	v_pk_mul_f32 v[94:95], v[94:95], v[100:101] op_sel_hi:[1,0]
	v_pk_mul_f32 v[96:97], v[96:97], v[100:101] op_sel_hi:[1,0]
	v_pk_fma_f32 v[104:105], v[142:143], v[94:95], v[174:175]
	v_mov_b32_e32 v94, 0x7fc00000
	v_pk_fma_f32 v[96:97], v[144:145], v[96:97], v[176:177]
	v_cndmask_b32_e32 v101, v104, v94, vcc
	v_lshl_add_u64 v[102:103], s[0:1], 0, v[102:103]
	v_cndmask_b32_e32 v95, v96, v94, vcc
	v_cndmask_b32_e32 v99, v97, v94, vcc
	v_cndmask_b32_e32 v104, v105, v94, vcc
	v_cvt_pk_bf16_f32 v96, v101, v104
	v_cvt_pk_bf16_f32 v97, v95, v99
	v_lshl_add_u64 v[102:103], v[214:215], 1, v[102:103]
	v_pk_mul_f32 v[90:91], v[90:91], v[100:101] op_sel_hi:[1,0]
	v_mov_b32_e32 v240, v96
	v_mov_b32_e32 v241, v97
	v_mul_f32_e32 v96, v104, v104
	v_mul_f32_e32 v97, v99, v99
	v_pk_mul_f32 v[92:93], v[92:93], v[100:101] op_sel_hi:[1,0]
	v_pk_fma_f32 v[90:91], v[134:135], v[90:91], v[170:171]
	v_fmac_f32_e32 v96, v101, v101
	v_fmac_f32_e32 v97, v95, v95
	v_pk_fma_f32 v[92:93], v[136:137], v[92:93], v[172:173]
	v_cndmask_b32_e32 v91, v91, v94, vcc
	v_add_f32_e32 v95, v96, v97
	v_cndmask_b32_e32 v93, v93, v94, vcc
	v_cndmask_b32_e32 v96, v90, v94, vcc
	v_cvt_pk_bf16_f32 v90, v96, v91
	v_mul_f32_e32 v91, v91, v91
	v_cndmask_b32_e32 v92, v92, v94, vcc
	v_fmac_f32_e32 v91, v96, v96
	v_mul_f32_e32 v96, v93, v93
	v_pk_mul_f32 v[88:89], v[88:89], v[100:101] op_sel_hi:[1,0]
	v_pk_mul_f32 v[86:87], v[86:87], v[100:101] op_sel_hi:[1,0]
	v_fmac_f32_e32 v96, v92, v92
	v_pk_fma_f32 v[88:89], v[132:133], v[88:89], v[168:169]
	v_pk_fma_f32 v[86:87], v[130:131], v[86:87], v[166:167]
	v_add_f32_e32 v91, v91, v96
	v_cndmask_b32_e32 v89, v89, v94, vcc
	v_cndmask_b32_e32 v87, v87, v94, vcc
	v_add_f32_e32 v91, v95, v91
	v_cndmask_b32_e32 v88, v88, v94, vcc
	v_cndmask_b32_e32 v86, v86, v94, vcc
	v_mul_f32_e32 v95, v87, v87
	v_mul_f32_e32 v96, v89, v89
	v_pk_mul_f32 v[84:85], v[84:85], v[100:101] op_sel_hi:[1,0]
	v_pk_mul_f32 v[82:83], v[82:83], v[100:101] op_sel_hi:[1,0]
	v_fmac_f32_e32 v95, v86, v86
	v_fmac_f32_e32 v96, v88, v88
	v_pk_fma_f32 v[84:85], v[124:125], v[84:85], v[164:165]
	v_pk_fma_f32 v[82:83], v[122:123], v[82:83], v[162:163]
	v_add_f32_e32 v95, v95, v96
	v_cndmask_b32_e32 v96, v85, v94, vcc
	v_cndmask_b32_e32 v99, v83, v94, vcc
	v_add_f32_e32 v91, v95, v91
	v_cndmask_b32_e32 v95, v84, v94, vcc
	v_cndmask_b32_e32 v97, v82, v94, vcc
	v_mul_f32_e32 v82, v99, v99
	v_mul_f32_e32 v83, v96, v96
	v_fmac_f32_e32 v82, v97, v97
	v_fmac_f32_e32 v83, v95, v95
	v_add_f32_e32 v82, v82, v83
	v_add_f32_e32 v82, v82, v91
	ds_bpermute_b32 v83, v1, v82
	v_cvt_pk_bf16_f32 v91, v92, v93
	v_mov_b32_e32 v242, v90
	v_mov_b32_e32 v243, v91
	s_nop 1
	v_permlane32_swap_b32_e32 v240, v242
	v_permlane32_swap_b32_e32 v241, v243
	s_nop 0
	v_permlane16_swap_b32_e32 v240, v242
	v_permlane16_swap_b32_e32 v241, v243
	v_lshl_add_u64 v[236:237], v[102:103], 0, v[238:239]
	global_store_dwordx4 v[236:237], v[240:243], off
	v_cvt_pk_bf16_f32 v84, v86, v87
	v_cvt_pk_bf16_f32 v85, v88, v89
	s_waitcnt lgkmcnt(0)
	v_add_f32_e32 v82, v82, v83
	ds_bpermute_b32 v83, v233, v82
	v_mov_b32_e32 v244, v84
	v_mov_b32_e32 v245, v85
	v_cvt_pk_bf16_f32 v84, v97, v99
	v_cvt_pk_bf16_f32 v85, v95, v96
	v_mov_b32_e32 v246, v84
	v_mov_b32_e32 v247, v85
	s_nop 1
	v_permlane32_swap_b32_e32 v244, v246
	v_permlane32_swap_b32_e32 v245, v247
	s_nop 0
	v_permlane16_swap_b32_e32 v244, v246
	v_permlane16_swap_b32_e32 v245, v247
	v_lshl_add_u64 v[236:237], v[102:103], 0, v[238:239]
	global_store_dwordx4 v[236:237], v[244:247], off offset:256
	s_and_saveexec_b64 s[2:3], s[4:5]
	s_cbranch_execz .LBB0_264
	v_lshl_add_u32 v84, v98, 4, s31
	s_waitcnt lgkmcnt(0)
	v_add_f32_e32 v82, v82, v83
	ds_write_b32 v84, v82 offset:16384
.LBB0_264:
	s_or_b64 exec, exec, s[2:3]
	ds_read_b32 v84, v210 offset:8384
	v_or_b32_e32 v82, 48, v225
	v_add_u32_e32 v86, s30, v82
	v_ashrrev_i32_e32 v87, 31, v86
	s_waitcnt lgkmcnt(0)
	v_pk_mul_f32 v[80:81], v[80:81], v[84:85] op_sel_hi:[1,0]
	s_nop 0
	v_pk_fma_f32 v[80:81], v[144:145], v[80:81], v[160:161]
	v_pk_mul_f32 v[78:79], v[78:79], v[84:85] op_sel_hi:[1,0]
	v_cndmask_b32_e32 v83, v80, v94, vcc
	v_cndmask_b32_e32 v85, v81, v94, vcc
	v_lshlrev_b64 v[80:81], 11, v[86:87]
	v_pk_fma_f32 v[78:79], v[142:143], v[78:79], v[158:159]
	v_lshl_add_u64 v[80:81], s[0:1], 0, v[80:81]
	v_cndmask_b32_e32 v88, v78, v94, vcc
	v_cndmask_b32_e32 v89, v79, v94, vcc
	v_cvt_pk_bf16_f32 v78, v88, v89
	v_cvt_pk_bf16_f32 v79, v83, v85
	v_lshl_add_u64 v[80:81], v[214:215], 1, v[80:81]
	v_pk_mul_f32 v[74:75], v[74:75], v[84:85] op_sel_hi:[1,0]
	v_mov_b32_e32 v240, v78
	v_mov_b32_e32 v241, v79
	v_mul_f32_e32 v78, v89, v89
	v_mul_f32_e32 v79, v85, v85
	v_pk_mul_f32 v[76:77], v[76:77], v[84:85] op_sel_hi:[1,0]
	v_pk_fma_f32 v[74:75], v[134:135], v[74:75], v[154:155]
	v_fmac_f32_e32 v78, v88, v88
	v_fmac_f32_e32 v79, v83, v83
	v_pk_fma_f32 v[76:77], v[136:137], v[76:77], v[156:157]
	v_cndmask_b32_e32 v75, v75, v94, vcc
	v_add_f32_e32 v78, v78, v79
	v_cndmask_b32_e32 v77, v77, v94, vcc
	v_cndmask_b32_e32 v79, v74, v94, vcc
	v_cvt_pk_bf16_f32 v74, v79, v75
	v_mul_f32_e32 v75, v75, v75
	v_cndmask_b32_e32 v76, v76, v94, vcc
	v_fmac_f32_e32 v75, v79, v79
	v_mul_f32_e32 v79, v77, v77
	v_pk_mul_f32 v[72:73], v[72:73], v[84:85] op_sel_hi:[1,0]
	v_pk_mul_f32 v[70:71], v[70:71], v[84:85] op_sel_hi:[1,0]
	v_fmac_f32_e32 v79, v76, v76
	v_pk_fma_f32 v[72:73], v[132:133], v[72:73], v[152:153]
	v_pk_fma_f32 v[70:71], v[130:131], v[70:71], v[150:151]
	v_add_f32_e32 v75, v75, v79
	v_cndmask_b32_e32 v73, v73, v94, vcc
	v_cndmask_b32_e32 v71, v71, v94, vcc
	v_add_f32_e32 v75, v78, v75
	v_cndmask_b32_e32 v72, v72, v94, vcc
	v_cndmask_b32_e32 v70, v70, v94, vcc
	v_mul_f32_e32 v78, v71, v71
	v_mul_f32_e32 v79, v73, v73
	v_pk_mul_f32 v[68:69], v[68:69], v[84:85] op_sel_hi:[1,0]
	v_pk_mul_f32 v[66:67], v[66:67], v[84:85] op_sel_hi:[1,0]
	v_fmac_f32_e32 v78, v70, v70
	v_fmac_f32_e32 v79, v72, v72
	v_pk_fma_f32 v[68:69], v[124:125], v[68:69], v[148:149]
	v_pk_fma_f32 v[66:67], v[122:123], v[66:67], v[146:147]
	v_add_f32_e32 v78, v78, v79
	v_cndmask_b32_e32 v79, v69, v94, vcc
	v_cndmask_b32_e32 v84, v67, v94, vcc
	v_add_f32_e32 v75, v78, v75
	v_cndmask_b32_e32 v78, v68, v94, vcc
	v_cndmask_b32_e32 v83, v66, v94, vcc
	v_mul_f32_e32 v66, v84, v84
	v_mul_f32_e32 v67, v79, v79
	v_fmac_f32_e32 v66, v83, v83
	v_fmac_f32_e32 v67, v78, v78
	v_add_f32_e32 v66, v66, v67
	v_add_f32_e32 v66, v66, v75
	ds_bpermute_b32 v67, v1, v66
	v_cvt_pk_bf16_f32 v75, v76, v77
	v_mov_b32_e32 v242, v74
	v_mov_b32_e32 v243, v75
	s_nop 1
	v_permlane32_swap_b32_e32 v240, v242
	v_permlane32_swap_b32_e32 v241, v243
	s_nop 0
	v_permlane16_swap_b32_e32 v240, v242
	v_permlane16_swap_b32_e32 v241, v243
	v_lshl_add_u64 v[236:237], v[80:81], 0, v[238:239]
	global_store_dwordx4 v[236:237], v[240:243], off
	v_cvt_pk_bf16_f32 v68, v70, v71
	v_cvt_pk_bf16_f32 v69, v72, v73
	s_waitcnt lgkmcnt(0)
	v_add_f32_e32 v66, v66, v67
	ds_bpermute_b32 v67, v233, v66
	v_mov_b32_e32 v244, v68
	v_mov_b32_e32 v245, v69
	v_cvt_pk_bf16_f32 v68, v83, v84
	v_cvt_pk_bf16_f32 v69, v78, v79
	v_mov_b32_e32 v246, v68
	v_mov_b32_e32 v247, v69
	s_nop 1
	v_permlane32_swap_b32_e32 v244, v246
	v_permlane32_swap_b32_e32 v245, v247
	s_nop 0
	v_permlane16_swap_b32_e32 v244, v246
	v_permlane16_swap_b32_e32 v245, v247
	v_lshl_add_u64 v[236:237], v[80:81], 0, v[238:239]
	global_store_dwordx4 v[236:237], v[244:247], off offset:256
	s_and_saveexec_b64 s[2:3], s[4:5]
	s_cbranch_execz .LBB0_266
	v_lshl_add_u32 v68, v82, 4, s31
	s_waitcnt lgkmcnt(0)
	v_add_f32_e32 v66, v66, v67
	ds_write_b32 v68, v66 offset:16384
.LBB0_266:
	s_or_b64 exec, exec, s[2:3]
	s_add_i32 s2, s28, 0x80
	v_or_b32_e32 v66, s2, v219
	v_add_u32_e32 v74, s30, v66
	v_ashrrev_i32_e32 v75, 31, v74
	v_lshlrev_b64 v[68:69], 12, v[74:75]
	v_lshl_add_u64 v[76:77], v[216:217], 0, v[68:69]
	global_load_dwordx4 v[70:73], v[76:77], off
	s_waitcnt lgkmcnt(0)
	v_add_u32_e32 v67, s28, v219
	v_lshl_add_u32 v67, v67, 2, 0
	ds_read_b32 v78, v67 offset:8704
	v_lshlrev_b64 v[74:75], 10, v[74:75]
	v_lshl_add_u64 v[74:75], v[74:75], 0, v[214:215]
	v_mov_b32_e32 v68, 0x7fc00000
	v_lshl_add_u64 v[74:75], v[74:75], 1, s[0:1]
	s_waitcnt lgkmcnt(0)
	v_pk_mul_f32 v[64:65], v[64:65], v[78:79] op_sel_hi:[1,0]
	v_pk_mul_f32 v[62:63], v[62:63], v[78:79] op_sel_hi:[1,0]
	v_pk_mul_f32 v[60:61], v[60:61], v[78:79] op_sel_hi:[1,0]
	v_pk_mul_f32 v[58:59], v[58:59], v[78:79] op_sel_hi:[1,0]
	v_pk_mul_f32 v[56:57], v[56:57], v[78:79] op_sel_hi:[1,0]
	v_pk_mul_f32 v[54:55], v[54:55], v[78:79] op_sel_hi:[1,0]
	v_pk_mul_f32 v[52:53], v[52:53], v[78:79] op_sel_hi:[1,0]
	v_pk_mul_f32 v[50:51], v[50:51], v[78:79] op_sel_hi:[1,0]
	s_waitcnt vmcnt(0)
	v_pk_fma_f32 v[64:65], v[144:145], v[64:65], v[72:73]
	v_pk_fma_f32 v[62:63], v[142:143], v[62:63], v[70:71]
	v_cndmask_b32_e32 v69, v64, v68, vcc
	v_cndmask_b32_e32 v70, v65, v68, vcc
	v_cndmask_b32_e32 v71, v62, v68, vcc
	v_cndmask_b32_e32 v72, v63, v68, vcc
	v_cvt_pk_bf16_f32 v62, v71, v72
	v_cvt_pk_bf16_f32 v63, v69, v70
	v_mov_b32_e32 v240, v62
	v_mov_b32_e32 v241, v63
	global_load_dwordx4 v[62:65], v[76:77], off offset:64
	v_mul_f32_e32 v72, v72, v72
	v_mul_f32_e32 v70, v70, v70
	v_fmac_f32_e32 v72, v71, v71
	v_fmac_f32_e32 v70, v69, v69
	v_add_f32_e32 v69, v72, v70
	s_waitcnt vmcnt(0)
	v_pk_fma_f32 v[60:61], v[136:137], v[60:61], v[64:65]
	v_pk_fma_f32 v[58:59], v[134:135], v[58:59], v[62:63]
	v_cndmask_b32_e32 v62, v60, v68, vcc
	v_cndmask_b32_e32 v63, v61, v68, vcc
	v_cndmask_b32_e32 v64, v58, v68, vcc
	v_cndmask_b32_e32 v65, v59, v68, vcc
	v_cvt_pk_bf16_f32 v58, v64, v65
	v_cvt_pk_bf16_f32 v59, v62, v63
	v_mov_b32_e32 v242, v58
	v_mov_b32_e32 v243, v59
	s_nop 1
	v_permlane32_swap_b32_e32 v240, v242
	v_permlane32_swap_b32_e32 v241, v243
	s_nop 0
	v_permlane16_swap_b32_e32 v240, v242
	v_permlane16_swap_b32_e32 v241, v243
	v_lshl_add_u64 v[236:237], v[74:75], 0, v[238:239]
	global_store_dwordx4 v[236:237], v[240:243], off
	global_load_dwordx4 v[58:61], v[76:77], off offset:512
	v_mul_f32_e32 v65, v65, v65
	v_mul_f32_e32 v63, v63, v63
	v_fmac_f32_e32 v65, v64, v64
	v_fmac_f32_e32 v63, v62, v62
	v_add_f32_e32 v62, v65, v63
	v_add_f32_e32 v62, v69, v62
	s_waitcnt vmcnt(0)
	v_pk_fma_f32 v[56:57], v[132:133], v[56:57], v[60:61]
	v_pk_fma_f32 v[54:55], v[130:131], v[54:55], v[58:59]
	v_cndmask_b32_e32 v58, v56, v68, vcc
	v_cndmask_b32_e32 v59, v57, v68, vcc
	v_cndmask_b32_e32 v60, v54, v68, vcc
	v_cndmask_b32_e32 v61, v55, v68, vcc
	v_cvt_pk_bf16_f32 v54, v60, v61
	v_cvt_pk_bf16_f32 v55, v58, v59
	v_mov_b32_e32 v244, v54
	v_mov_b32_e32 v245, v55
	global_load_dwordx4 v[54:57], v[76:77], off offset:576
	v_mul_f32_e32 v61, v61, v61
	v_mul_f32_e32 v59, v59, v59
	v_fmac_f32_e32 v61, v60, v60
	v_fmac_f32_e32 v59, v58, v58
	v_add_f32_e32 v58, v61, v59
	v_add_f32_e32 v58, v62, v58
	s_waitcnt vmcnt(0)
	v_pk_fma_f32 v[52:53], v[124:125], v[52:53], v[56:57]
	v_pk_fma_f32 v[50:51], v[122:123], v[50:51], v[54:55]
	v_cndmask_b32_e32 v53, v53, v68, vcc
	v_cndmask_b32_e32 v55, v51, v68, vcc
	v_cndmask_b32_e32 v54, v52, v68, vcc
	v_cndmask_b32_e32 v52, v50, v68, vcc
	v_mul_f32_e32 v50, v55, v55
	v_mul_f32_e32 v51, v53, v53
	v_fmac_f32_e32 v50, v52, v52
	v_fmac_f32_e32 v51, v54, v54
	v_add_f32_e32 v50, v50, v51
	v_add_f32_e32 v50, v58, v50
	ds_bpermute_b32 v51, v1, v50
	v_cvt_pk_bf16_f32 v52, v52, v55
	v_cvt_pk_bf16_f32 v53, v54, v53
	v_mov_b32_e32 v246, v52
	v_mov_b32_e32 v247, v53
	s_nop 1
	v_permlane32_swap_b32_e32 v244, v246
	v_permlane32_swap_b32_e32 v245, v247
	s_nop 0
	v_permlane16_swap_b32_e32 v244, v246
	v_permlane16_swap_b32_e32 v245, v247
	v_lshl_add_u64 v[236:237], v[74:75], 0, v[238:239]
	global_store_dwordx4 v[236:237], v[244:247], off offset:256
	s_waitcnt lgkmcnt(0)
	v_add_f32_e32 v50, v50, v51
	ds_bpermute_b32 v51, v233, v50
	s_and_saveexec_b64 s[2:3], s[4:5]
	s_cbranch_execz .LBB0_268
	v_lshl_add_u32 v52, v66, 4, s31
	s_waitcnt lgkmcnt(0)
	v_add_f32_e32 v50, v50, v51
	ds_write_b32 v52, v50 offset:16384
.LBB0_268:
	s_or_b64 exec, exec, s[2:3]
	v_or_b32_e32 v50, 16, v66
	v_add_u32_e32 v56, s30, v50
	v_ashrrev_i32_e32 v57, 31, v56
	v_lshlrev_b64 v[52:53], 12, v[56:57]
	v_lshl_add_u64 v[58:59], v[216:217], 0, v[52:53]
	global_load_dwordx4 v[52:55], v[58:59], off
	ds_read_b32 v60, v67 offset:8768
	v_lshlrev_b64 v[56:57], 10, v[56:57]
	v_lshl_add_u64 v[56:57], v[56:57], 0, v[214:215]
	v_lshl_add_u64 v[56:57], v[56:57], 1, s[0:1]
	s_waitcnt lgkmcnt(0)
	v_pk_mul_f32 v[48:49], v[48:49], v[60:61] op_sel_hi:[1,0]
	v_pk_mul_f32 v[46:47], v[46:47], v[60:61] op_sel_hi:[1,0]
	v_pk_mul_f32 v[44:45], v[44:45], v[60:61] op_sel_hi:[1,0]
	v_pk_mul_f32 v[42:43], v[42:43], v[60:61] op_sel_hi:[1,0]
	v_pk_mul_f32 v[40:41], v[40:41], v[60:61] op_sel_hi:[1,0]
	v_pk_mul_f32 v[38:39], v[38:39], v[60:61] op_sel_hi:[1,0]
	v_pk_mul_f32 v[36:37], v[36:37], v[60:61] op_sel_hi:[1,0]
	v_pk_mul_f32 v[34:35], v[34:35], v[60:61] op_sel_hi:[1,0]
	s_waitcnt vmcnt(0)
	v_pk_fma_f32 v[48:49], v[144:145], v[48:49], v[54:55]
	v_pk_fma_f32 v[46:47], v[142:143], v[46:47], v[52:53]
	v_cndmask_b32_e32 v51, v48, v68, vcc
	v_cndmask_b32_e32 v52, v49, v68, vcc
	v_cndmask_b32_e32 v53, v46, v68, vcc
	v_cndmask_b32_e32 v54, v47, v68, vcc
	v_cvt_pk_bf16_f32 v46, v53, v54
	v_cvt_pk_bf16_f32 v47, v51, v52
	v_mov_b32_e32 v240, v46
	v_mov_b32_e32 v241, v47
	global_load_dwordx4 v[46:49], v[58:59], off offset:64
	v_mul_f32_e32 v54, v54, v54
	v_mul_f32_e32 v52, v52, v52
	v_fmac_f32_e32 v54, v53, v53
	v_fmac_f32_e32 v52, v51, v51
	v_add_f32_e32 v51, v54, v52
	s_waitcnt vmcnt(0)
	v_pk_fma_f32 v[44:45], v[136:137], v[44:45], v[48:49]
	v_pk_fma_f32 v[42:43], v[134:135], v[42:43], v[46:47]
	v_cndmask_b32_e32 v46, v44, v68, vcc
	v_cndmask_b32_e32 v47, v45, v68, vcc
	v_cndmask_b32_e32 v48, v42, v68, vcc
	v_cndmask_b32_e32 v49, v43, v68, vcc
	v_cvt_pk_bf16_f32 v42, v48, v49
	v_cvt_pk_bf16_f32 v43, v46, v47
	v_mov_b32_e32 v242, v42
	v_mov_b32_e32 v243, v43
	s_nop 1
	v_permlane32_swap_b32_e32 v240, v242
	v_permlane32_swap_b32_e32 v241, v243
	s_nop 0
	v_permlane16_swap_b32_e32 v240, v242
	v_permlane16_swap_b32_e32 v241, v243
	v_lshl_add_u64 v[236:237], v[56:57], 0, v[238:239]
	global_store_dwordx4 v[236:237], v[240:243], off
	global_load_dwordx4 v[42:45], v[58:59], off offset:512
	v_mul_f32_e32 v49, v49, v49
	v_mul_f32_e32 v47, v47, v47
	v_fmac_f32_e32 v49, v48, v48
	v_fmac_f32_e32 v47, v46, v46
	v_add_f32_e32 v46, v49, v47
	v_add_f32_e32 v46, v51, v46
	s_waitcnt vmcnt(0)
	v_pk_fma_f32 v[40:41], v[132:133], v[40:41], v[44:45]
	v_pk_fma_f32 v[38:39], v[130:131], v[38:39], v[42:43]
	v_cndmask_b32_e32 v42, v40, v68, vcc
	v_cndmask_b32_e32 v43, v41, v68, vcc
	v_cndmask_b32_e32 v44, v38, v68, vcc
	v_cndmask_b32_e32 v45, v39, v68, vcc
	v_cvt_pk_bf16_f32 v38, v44, v45
	v_cvt_pk_bf16_f32 v39, v42, v43
	v_mov_b32_e32 v244, v38
	v_mov_b32_e32 v245, v39
	global_load_dwordx4 v[38:41], v[58:59], off offset:576
	v_mul_f32_e32 v45, v45, v45
	v_mul_f32_e32 v43, v43, v43
	v_fmac_f32_e32 v45, v44, v44
	v_fmac_f32_e32 v43, v42, v42
	v_add_f32_e32 v42, v45, v43
	v_add_f32_e32 v42, v46, v42
	s_waitcnt vmcnt(0)
	v_pk_fma_f32 v[36:37], v[124:125], v[36:37], v[40:41]
	v_pk_fma_f32 v[34:35], v[122:123], v[34:35], v[38:39]
	v_cndmask_b32_e32 v37, v37, v68, vcc
	v_cndmask_b32_e32 v39, v35, v68, vcc
	v_cndmask_b32_e32 v38, v36, v68, vcc
	v_cndmask_b32_e32 v36, v34, v68, vcc
	v_mul_f32_e32 v34, v39, v39
	v_mul_f32_e32 v35, v37, v37
	v_fmac_f32_e32 v34, v36, v36
	v_fmac_f32_e32 v35, v38, v38
	v_add_f32_e32 v34, v34, v35
	v_add_f32_e32 v34, v42, v34
	ds_bpermute_b32 v35, v1, v34
	v_cvt_pk_bf16_f32 v36, v36, v39
	v_cvt_pk_bf16_f32 v37, v38, v37
	v_mov_b32_e32 v246, v36
	v_mov_b32_e32 v247, v37
	s_nop 1
	v_permlane32_swap_b32_e32 v244, v246
	v_permlane32_swap_b32_e32 v245, v247
	s_nop 0
	v_permlane16_swap_b32_e32 v244, v246
	v_permlane16_swap_b32_e32 v245, v247
	v_lshl_add_u64 v[236:237], v[56:57], 0, v[238:239]
	global_store_dwordx4 v[236:237], v[244:247], off offset:256
	s_waitcnt lgkmcnt(0)
	v_add_f32_e32 v34, v34, v35
	ds_bpermute_b32 v35, v233, v34
	s_and_saveexec_b64 s[2:3], s[4:5]
	s_cbranch_execz .LBB0_270
	v_lshl_add_u32 v36, v50, 4, s31
	s_waitcnt lgkmcnt(0)
	v_add_f32_e32 v34, v34, v35
	ds_write_b32 v36, v34 offset:16384
.LBB0_270:
	s_or_b64 exec, exec, s[2:3]
	s_waitcnt lgkmcnt(0)
	v_or_b32_e32 v35, 32, v66
	v_add_u32_e32 v40, s30, v35
	v_ashrrev_i32_e32 v41, 31, v40
	v_lshlrev_b64 v[36:37], 12, v[40:41]
	v_lshl_add_u64 v[42:43], v[216:217], 0, v[36:37]
	global_load_dwordx4 v[36:39], v[42:43], off
	ds_read_b32 v44, v210 offset:8832
	v_lshlrev_b64 v[40:41], 10, v[40:41]
	v_lshl_add_u64 v[40:41], v[40:41], 0, v[214:215]
	v_mov_b32_e32 v34, 0x7fc00000
	v_lshl_add_u64 v[40:41], v[40:41], 1, s[0:1]
	s_waitcnt lgkmcnt(0)
	v_pk_mul_f32 v[32:33], v[32:33], v[44:45] op_sel_hi:[1,0]
	v_pk_mul_f32 v[30:31], v[30:31], v[44:45] op_sel_hi:[1,0]
	v_pk_mul_f32 v[28:29], v[28:29], v[44:45] op_sel_hi:[1,0]
	v_pk_mul_f32 v[26:27], v[26:27], v[44:45] op_sel_hi:[1,0]
	v_pk_mul_f32 v[24:25], v[24:25], v[44:45] op_sel_hi:[1,0]
	v_pk_mul_f32 v[22:23], v[22:23], v[44:45] op_sel_hi:[1,0]
	v_pk_mul_f32 v[20:21], v[20:21], v[44:45] op_sel_hi:[1,0]
	v_pk_mul_f32 v[18:19], v[18:19], v[44:45] op_sel_hi:[1,0]
	s_waitcnt vmcnt(0)
	v_pk_fma_f32 v[32:33], v[144:145], v[32:33], v[38:39]
	v_pk_fma_f32 v[30:31], v[142:143], v[30:31], v[36:37]
	v_cndmask_b32_e32 v36, v32, v34, vcc
	v_cndmask_b32_e32 v37, v33, v34, vcc
	v_cndmask_b32_e32 v38, v30, v34, vcc
	v_cndmask_b32_e32 v39, v31, v34, vcc
	v_cvt_pk_bf16_f32 v30, v38, v39
	v_cvt_pk_bf16_f32 v31, v36, v37
	v_mov_b32_e32 v240, v30
	v_mov_b32_e32 v241, v31
	global_load_dwordx4 v[30:33], v[42:43], off offset:64
	v_mul_f32_e32 v39, v39, v39
	v_mul_f32_e32 v37, v37, v37
	v_fmac_f32_e32 v39, v38, v38
	v_fmac_f32_e32 v37, v36, v36
	v_add_f32_e32 v36, v39, v37
	s_waitcnt vmcnt(0)
	v_pk_fma_f32 v[28:29], v[136:137], v[28:29], v[32:33]
	v_pk_fma_f32 v[26:27], v[134:135], v[26:27], v[30:31]
	v_cndmask_b32_e32 v30, v28, v34, vcc
	v_cndmask_b32_e32 v31, v29, v34, vcc
	v_cndmask_b32_e32 v32, v26, v34, vcc
	v_cndmask_b32_e32 v33, v27, v34, vcc
	v_cvt_pk_bf16_f32 v26, v32, v33
	v_cvt_pk_bf16_f32 v27, v30, v31
	v_mov_b32_e32 v242, v26
	v_mov_b32_e32 v243, v27
	s_nop 1
	v_permlane32_swap_b32_e32 v240, v242
	v_permlane32_swap_b32_e32 v241, v243
	s_nop 0
	v_permlane16_swap_b32_e32 v240, v242
	v_permlane16_swap_b32_e32 v241, v243
	v_lshl_add_u64 v[236:237], v[40:41], 0, v[238:239]
	global_store_dwordx4 v[236:237], v[240:243], off
	global_load_dwordx4 v[26:29], v[42:43], off offset:512
	v_mul_f32_e32 v33, v33, v33
	v_mul_f32_e32 v31, v31, v31
	v_fmac_f32_e32 v33, v32, v32
	v_fmac_f32_e32 v31, v30, v30
	v_add_f32_e32 v30, v33, v31
	v_add_f32_e32 v30, v36, v30
	s_waitcnt vmcnt(0)
	v_pk_fma_f32 v[24:25], v[132:133], v[24:25], v[28:29]
	v_pk_fma_f32 v[22:23], v[130:131], v[22:23], v[26:27]
	v_cndmask_b32_e32 v26, v24, v34, vcc
	v_cndmask_b32_e32 v27, v25, v34, vcc
	v_cndmask_b32_e32 v28, v22, v34, vcc
	v_cndmask_b32_e32 v29, v23, v34, vcc
	v_cvt_pk_bf16_f32 v22, v28, v29
	v_cvt_pk_bf16_f32 v23, v26, v27
	v_mov_b32_e32 v244, v22
	v_mov_b32_e32 v245, v23
	global_load_dwordx4 v[22:25], v[42:43], off offset:576
	v_mul_f32_e32 v29, v29, v29
	v_mul_f32_e32 v27, v27, v27
	v_fmac_f32_e32 v29, v28, v28
	v_fmac_f32_e32 v27, v26, v26
	v_add_f32_e32 v26, v29, v27
	v_add_f32_e32 v26, v30, v26
	s_waitcnt vmcnt(0)
	v_pk_fma_f32 v[20:21], v[124:125], v[20:21], v[24:25]
	v_pk_fma_f32 v[18:19], v[122:123], v[18:19], v[22:23]
	v_cndmask_b32_e32 v21, v21, v34, vcc
	v_cndmask_b32_e32 v23, v19, v34, vcc
	v_cndmask_b32_e32 v22, v20, v34, vcc
	v_cndmask_b32_e32 v20, v18, v34, vcc
	v_mul_f32_e32 v18, v23, v23
	v_mul_f32_e32 v19, v21, v21
	v_fmac_f32_e32 v18, v20, v20
	v_fmac_f32_e32 v19, v22, v22
	v_add_f32_e32 v18, v18, v19
	v_add_f32_e32 v18, v26, v18
	ds_bpermute_b32 v19, v1, v18
	v_cvt_pk_bf16_f32 v20, v20, v23
	v_cvt_pk_bf16_f32 v21, v22, v21
	v_mov_b32_e32 v246, v20
	v_mov_b32_e32 v247, v21
	s_nop 1
	v_permlane32_swap_b32_e32 v244, v246
	v_permlane32_swap_b32_e32 v245, v247
	s_nop 0
	v_permlane16_swap_b32_e32 v244, v246
	v_permlane16_swap_b32_e32 v245, v247
	v_lshl_add_u64 v[236:237], v[40:41], 0, v[238:239]
	global_store_dwordx4 v[236:237], v[244:247], off offset:256
	s_waitcnt lgkmcnt(0)
	v_add_f32_e32 v18, v18, v19
	ds_bpermute_b32 v19, v233, v18
	s_and_saveexec_b64 s[2:3], s[4:5]
	s_cbranch_execz .LBB0_272
	v_lshl_add_u32 v20, v35, 4, s31
	s_waitcnt lgkmcnt(0)
	v_add_f32_e32 v18, v18, v19
	ds_write_b32 v20, v18 offset:16384
.LBB0_272:
	s_or_b64 exec, exec, s[2:3]
	v_or_b32_e32 v18, 48, v66
	v_add_u32_e32 v24, s30, v18
	v_ashrrev_i32_e32 v25, 31, v24
	v_lshlrev_b64 v[20:21], 12, v[24:25]
	v_lshl_add_u64 v[26:27], v[216:217], 0, v[20:21]
	global_load_dwordx4 v[20:23], v[26:27], off
	ds_read_b32 v28, v67 offset:8896
	v_lshlrev_b64 v[24:25], 10, v[24:25]
	v_lshl_add_u64 v[24:25], v[24:25], 0, v[214:215]
	v_lshl_add_u64 v[24:25], v[24:25], 1, s[0:1]
	s_waitcnt lgkmcnt(0)
	v_pk_mul_f32 v[16:17], v[16:17], v[28:29] op_sel_hi:[1,0]
	v_pk_mul_f32 v[14:15], v[14:15], v[28:29] op_sel_hi:[1,0]
	v_pk_mul_f32 v[12:13], v[12:13], v[28:29] op_sel_hi:[1,0]
	v_pk_mul_f32 v[10:11], v[10:11], v[28:29] op_sel_hi:[1,0]
	v_pk_mul_f32 v[8:9], v[8:9], v[28:29] op_sel_hi:[1,0]
	v_pk_mul_f32 v[6:7], v[6:7], v[28:29] op_sel_hi:[1,0]
	v_pk_mul_f32 v[4:5], v[4:5], v[28:29] op_sel_hi:[1,0]
	v_pk_mul_f32 v[2:3], v[2:3], v[28:29] op_sel_hi:[1,0]
	s_waitcnt vmcnt(0)
	v_pk_fma_f32 v[16:17], v[144:145], v[16:17], v[22:23]
	v_pk_fma_f32 v[14:15], v[142:143], v[14:15], v[20:21]
	v_cndmask_b32_e32 v19, v16, v34, vcc
	v_cndmask_b32_e32 v20, v17, v34, vcc
	v_cndmask_b32_e32 v21, v14, v34, vcc
	v_cndmask_b32_e32 v22, v15, v34, vcc
	v_cvt_pk_bf16_f32 v14, v21, v22
	v_cvt_pk_bf16_f32 v15, v19, v20
	v_mov_b32_e32 v240, v14
	v_mov_b32_e32 v241, v15
	global_load_dwordx4 v[14:17], v[26:27], off offset:64
	v_mul_f32_e32 v22, v22, v22
	v_mul_f32_e32 v20, v20, v20
	v_fmac_f32_e32 v22, v21, v21
	v_fmac_f32_e32 v20, v19, v19
	v_add_f32_e32 v19, v22, v20
	s_waitcnt vmcnt(0)
	v_pk_fma_f32 v[12:13], v[136:137], v[12:13], v[16:17]
	v_pk_fma_f32 v[10:11], v[134:135], v[10:11], v[14:15]
	v_cndmask_b32_e32 v14, v12, v34, vcc
	v_cndmask_b32_e32 v15, v13, v34, vcc
	v_cndmask_b32_e32 v16, v10, v34, vcc
	v_cndmask_b32_e32 v17, v11, v34, vcc
	v_cvt_pk_bf16_f32 v10, v16, v17
	v_cvt_pk_bf16_f32 v11, v14, v15
	v_mov_b32_e32 v242, v10
	v_mov_b32_e32 v243, v11
	s_nop 1
	v_permlane32_swap_b32_e32 v240, v242
	v_permlane32_swap_b32_e32 v241, v243
	s_nop 0
	v_permlane16_swap_b32_e32 v240, v242
	v_permlane16_swap_b32_e32 v241, v243
	v_lshl_add_u64 v[236:237], v[24:25], 0, v[238:239]
	global_store_dwordx4 v[236:237], v[240:243], off
	global_load_dwordx4 v[10:13], v[26:27], off offset:512
	v_mul_f32_e32 v17, v17, v17
	v_mul_f32_e32 v15, v15, v15
	v_fmac_f32_e32 v17, v16, v16
	v_fmac_f32_e32 v15, v14, v14
	v_add_f32_e32 v14, v17, v15
	v_add_f32_e32 v14, v19, v14
	s_waitcnt vmcnt(0)
	v_pk_fma_f32 v[8:9], v[132:133], v[8:9], v[12:13]
	v_pk_fma_f32 v[6:7], v[130:131], v[6:7], v[10:11]
	v_cndmask_b32_e32 v10, v8, v34, vcc
	v_cndmask_b32_e32 v11, v9, v34, vcc
	v_cndmask_b32_e32 v12, v6, v34, vcc
	v_cndmask_b32_e32 v13, v7, v34, vcc
	v_cvt_pk_bf16_f32 v6, v12, v13
	v_cvt_pk_bf16_f32 v7, v10, v11
	v_mov_b32_e32 v244, v6
	v_mov_b32_e32 v245, v7
	global_load_dwordx4 v[6:9], v[26:27], off offset:576
	v_mul_f32_e32 v13, v13, v13
	v_mul_f32_e32 v11, v11, v11
	v_fmac_f32_e32 v13, v12, v12
	v_fmac_f32_e32 v11, v10, v10
	v_add_f32_e32 v10, v13, v11
	v_add_f32_e32 v10, v14, v10
	s_waitcnt vmcnt(0)
	v_pk_fma_f32 v[4:5], v[124:125], v[4:5], v[8:9]
	v_pk_fma_f32 v[2:3], v[122:123], v[2:3], v[6:7]
	v_cndmask_b32_e32 v5, v5, v34, vcc
	v_cndmask_b32_e32 v7, v3, v34, vcc
	v_cndmask_b32_e32 v6, v4, v34, vcc
	v_cndmask_b32_e32 v4, v2, v34, vcc
	v_mul_f32_e32 v2, v7, v7
	v_mul_f32_e32 v3, v5, v5
	v_fmac_f32_e32 v2, v4, v4
	v_fmac_f32_e32 v3, v6, v6
	v_add_f32_e32 v2, v2, v3
	v_add_f32_e32 v2, v10, v2
	ds_bpermute_b32 v3, v1, v2
	v_cvt_pk_bf16_f32 v4, v4, v7
	v_cvt_pk_bf16_f32 v5, v6, v5
	v_mov_b32_e32 v246, v4
	v_mov_b32_e32 v247, v5
	s_nop 1
	v_permlane32_swap_b32_e32 v244, v246
	v_permlane32_swap_b32_e32 v245, v247
	s_nop 0
	v_permlane16_swap_b32_e32 v244, v246
	v_permlane16_swap_b32_e32 v245, v247
	v_lshl_add_u64 v[236:237], v[24:25], 0, v[238:239]
	global_store_dwordx4 v[236:237], v[244:247], off offset:256
	s_waitcnt lgkmcnt(0)
	v_add_f32_e32 v2, v2, v3
	ds_bpermute_b32 v3, v233, v2
	s_and_saveexec_b64 s[0:1], s[4:5]
	s_cbranch_execz .LBB0_274
	v_lshl_add_u32 v4, v18, 4, s31
	s_waitcnt lgkmcnt(0)
	v_add_f32_e32 v2, v2, v3
	ds_write_b32 v4, v2 offset:16384

.LBB0_506:
	s_or_b64 exec, exec, s[2:3]
	s_waitcnt vmcnt(0) lgkmcnt(0)
	s_barrier
	v_mov_b32_e32 v146, 0
	ds_read_b32 v147, v146 offset:10240
	v_lshl_add_u32 v146, v222, 2, 0
	s_waitcnt lgkmcnt(0)
	ds_read_b32 v148, v146 offset:8192
	v_add_u32_e32 v218, s33, v222
	v_ashrrev_i32_e32 v219, 31, v218
	s_waitcnt vmcnt(36)
	v_or_b32_e32 v147, v147, v223
	v_lshlrev_b64 v[218:219], 11, v[218:219]
	s_waitcnt vmcnt(35)
	v_lshlrev_b32_e32 v220, 16, v214
	v_and_b32_e32 v221, 0xffff0000, v214
	v_lshlrev_b32_e32 v214, 16, v215
	v_and_b32_e32 v215, 0xffff0000, v215
	s_waitcnt lgkmcnt(0)
	v_pk_mul_f32 v[136:137], v[136:137], v[148:149] op_sel_hi:[1,0]
	v_pk_mul_f32 v[134:135], v[134:135], v[148:149] op_sel_hi:[1,0]
	s_waitcnt vmcnt(3)
	v_pk_fma_f32 v[136:137], v[144:145], v[136:137], v[214:215]
	v_pk_fma_f32 v[220:221], v[142:143], v[134:135], v[220:221]
	v_mov_b32_e32 v134, 0x7fc00000
	v_cmp_ne_u32_e32 vcc, 0, v147
	v_lshl_add_u64 v[214:215], s[0:1], 0, v[218:219]
	v_lshl_add_u64 v[214:215], v[150:151], 1, v[214:215]
	v_cndmask_b32_e32 v135, v136, v134, vcc
	v_cndmask_b32_e32 v147, v137, v134, vcc
	v_cndmask_b32_e32 v149, v220, v134, vcc
	v_cndmask_b32_e32 v216, v221, v134, vcc
	v_cvt_pk_bf16_f32 v136, v149, v216
	v_cvt_pk_bf16_f32 v137, v135, v147
	v_mbcnt_lo_u32_b32 v238, -1, 0
	v_mbcnt_hi_u32_b32 v238, -1, v238
	v_lshrrev_b32_e32 v238, 4, v238
	v_lshlrev_b32_e32 v238, 3, v238
	v_mov_b32_e32 v239, 0
	v_mov_b32_e32 v240, v136
	v_mov_b32_e32 v241, v137
	v_mul_f32_e32 v136, v216, v216
	v_mul_f32_e32 v137, v147, v147
	v_fmac_f32_e32 v136, v149, v149
	v_fmac_f32_e32 v137, v135, v135
	v_add_f32_e32 v135, v136, v137
	v_lshlrev_b32_e32 v136, 16, v212
	v_and_b32_e32 v137, 0xffff0000, v212
	v_pk_mul_f32 v[122:123], v[122:123], v[148:149] op_sel_hi:[1,0]
	v_lshlrev_b32_e32 v212, 16, v213
	v_and_b32_e32 v213, 0xffff0000, v213
	v_pk_mul_f32 v[124:125], v[124:125], v[148:149] op_sel_hi:[1,0]
	s_waitcnt vmcnt(3)
	v_pk_fma_f32 v[122:123], v[138:139], v[122:123], v[136:137]
	v_pk_fma_f32 v[124:125], v[140:141], v[124:125], v[212:213]
	v_cndmask_b32_e32 v123, v123, v134, vcc
	v_cndmask_b32_e32 v147, v124, v134, vcc
	v_cndmask_b32_e32 v149, v125, v134, vcc
	v_cndmask_b32_e32 v124, v122, v134, vcc
	v_cvt_pk_bf16_f32 v122, v124, v123
	v_mul_f32_e32 v123, v123, v123
	v_fmac_f32_e32 v123, v124, v124
	v_mul_f32_e32 v124, v149, v149
	v_fmac_f32_e32 v124, v147, v147
	v_add_f32_e32 v123, v123, v124
	v_lshlrev_b32_e32 v124, 16, v210
	v_and_b32_e32 v125, 0xffff0000, v210
	v_lshlrev_b32_e32 v136, 16, v211
	v_and_b32_e32 v137, 0xffff0000, v211
	v_pk_mul_f32 v[120:121], v[120:121], v[148:149] op_sel_hi:[1,0]
	v_pk_mul_f32 v[118:119], v[118:119], v[148:149] op_sel_hi:[1,0]
	s_waitcnt vmcnt(2)
	v_pk_fma_f32 v[120:121], v[132:133], v[120:121], v[136:137]
	v_pk_fma_f32 v[118:119], v[130:131], v[118:119], v[124:125]
	v_cndmask_b32_e32 v125, v121, v134, vcc
	v_cndmask_b32_e32 v136, v119, v134, vcc
	v_add_f32_e32 v123, v135, v123
	v_cndmask_b32_e32 v124, v120, v134, vcc
	v_cndmask_b32_e32 v135, v118, v134, vcc
	v_mul_f32_e32 v118, v136, v136
	v_mul_f32_e32 v119, v125, v125
	v_fmac_f32_e32 v118, v135, v135
	v_fmac_f32_e32 v119, v124, v124
	v_add_f32_e32 v118, v118, v119
	v_add_f32_e32 v123, v118, v123
	v_lshlrev_b32_e32 v118, 16, v208
	v_and_b32_e32 v119, 0xffff0000, v208
	v_lshlrev_b32_e32 v120, 16, v209
	v_and_b32_e32 v121, 0xffff0000, v209
	v_pk_mul_f32 v[116:117], v[116:117], v[148:149] op_sel_hi:[1,0]
	v_pk_mul_f32 v[114:115], v[114:115], v[148:149] op_sel_hi:[1,0]
	s_waitcnt vmcnt(1)
	v_pk_fma_f32 v[116:117], v[128:129], v[116:117], v[120:121]
	v_pk_fma_f32 v[114:115], v[126:127], v[114:115], v[118:119]
	v_cndmask_b32_e32 v119, v117, v134, vcc
	v_cndmask_b32_e32 v121, v115, v134, vcc
	v_cndmask_b32_e32 v118, v116, v134, vcc
	v_cndmask_b32_e32 v120, v114, v134, vcc
	v_mul_f32_e32 v114, v121, v121
	v_mul_f32_e32 v115, v119, v119
	v_fmac_f32_e32 v114, v120, v120
	v_fmac_f32_e32 v115, v118, v118
	v_add_f32_e32 v114, v114, v115
	v_add_f32_e32 v114, v114, v123
	ds_bpermute_b32 v115, v1, v114
	v_cvt_pk_bf16_f32 v123, v147, v149
	v_mov_b32_e32 v242, v122
	v_mov_b32_e32 v243, v123
	s_nop 1
	v_permlane32_swap_b32_e32 v240, v242
	v_permlane32_swap_b32_e32 v241, v243
	s_nop 0
	v_permlane16_swap_b32_e32 v240, v242
	v_permlane16_swap_b32_e32 v241, v243
	v_lshl_add_u64 v[236:237], v[214:215], 0, v[238:239]
	global_store_dwordx4 v[236:237], v[240:243], off
	v_cvt_pk_bf16_f32 v116, v135, v136
	v_cvt_pk_bf16_f32 v117, v124, v125
	s_waitcnt lgkmcnt(0)
	v_add_f32_e32 v114, v114, v115
	ds_bpermute_b32 v115, v233, v114
	v_mov_b32_e32 v244, v116
	v_mov_b32_e32 v245, v117
	v_cvt_pk_bf16_f32 v116, v120, v121
	v_cvt_pk_bf16_f32 v117, v118, v119
	v_mov_b32_e32 v246, v116
	v_mov_b32_e32 v247, v117
	s_nop 1
	v_permlane32_swap_b32_e32 v244, v246
	v_permlane32_swap_b32_e32 v245, v247
	s_nop 0
	v_permlane16_swap_b32_e32 v244, v246
	v_permlane16_swap_b32_e32 v245, v247
	v_lshl_add_u64 v[236:237], v[214:215], 0, v[238:239]
	global_store_dwordx4 v[236:237], v[244:247], off offset:256
	s_and_saveexec_b64 s[2:3], s[4:5]
	s_cbranch_execz .LBB0_508
	v_lshl_add_u32 v116, v222, 4, s34
	s_waitcnt lgkmcnt(0)
	v_add_f32_e32 v114, v114, v115
	ds_write_b32 v116, v114 offset:16384
.LBB0_508:
	s_or_b64 exec, exec, s[2:3]
	ds_read_b32 v116, v146 offset:8256
	v_or_b32_e32 v114, 16, v222
	v_add_u32_e32 v118, s33, v114
	v_ashrrev_i32_e32 v119, 31, v118
	v_lshlrev_b32_e32 v122, 16, v207
	v_and_b32_e32 v123, 0xffff0000, v207
	s_waitcnt lgkmcnt(0)
	v_pk_mul_f32 v[112:113], v[112:113], v[116:117] op_sel_hi:[1,0]
	v_lshlrev_b64 v[118:119], 11, v[118:119]
	v_lshlrev_b32_e32 v120, 16, v206
	v_and_b32_e32 v121, 0xffff0000, v206
	v_pk_mul_f32 v[110:111], v[110:111], v[116:117] op_sel_hi:[1,0]
	v_pk_fma_f32 v[112:113], v[144:145], v[112:113], v[122:123]
	v_pk_fma_f32 v[110:111], v[142:143], v[110:111], v[120:121]
	v_cndmask_b32_e32 v115, v112, v134, vcc
	v_cndmask_b32_e32 v117, v113, v134, vcc
	v_lshl_add_u64 v[112:113], s[0:1], 0, v[118:119]
	v_cndmask_b32_e32 v120, v110, v134, vcc
	v_cndmask_b32_e32 v121, v111, v134, vcc
	v_cvt_pk_bf16_f32 v110, v120, v121
	v_cvt_pk_bf16_f32 v111, v115, v117
	v_lshl_add_u64 v[112:113], v[150:151], 1, v[112:113]
	v_mov_b32_e32 v240, v110
	v_mov_b32_e32 v241, v111
	v_mul_f32_e32 v110, v121, v121
	v_mul_f32_e32 v111, v117, v117
	v_fmac_f32_e32 v110, v120, v120
	v_fmac_f32_e32 v111, v115, v115
	v_add_f32_e32 v115, v110, v111
	v_lshlrev_b32_e32 v110, 16, v204
	v_and_b32_e32 v111, 0xffff0000, v204
	v_pk_mul_f32 v[106:107], v[106:107], v[116:117] op_sel_hi:[1,0]
	v_lshlrev_b32_e32 v118, 16, v205
	v_and_b32_e32 v119, 0xffff0000, v205
	v_pk_mul_f32 v[108:109], v[108:109], v[116:117] op_sel_hi:[1,0]
	v_pk_fma_f32 v[106:107], v[138:139], v[106:107], v[110:111]
	v_pk_fma_f32 v[108:109], v[140:141], v[108:109], v[118:119]
	v_cndmask_b32_e32 v107, v107, v134, vcc
	v_cndmask_b32_e32 v117, v108, v134, vcc
	v_cndmask_b32_e32 v118, v109, v134, vcc
	v_cndmask_b32_e32 v108, v106, v134, vcc
	v_cvt_pk_bf16_f32 v106, v108, v107
	v_mul_f32_e32 v107, v107, v107
	v_fmac_f32_e32 v107, v108, v108
	v_mul_f32_e32 v108, v118, v118
	v_fmac_f32_e32 v108, v117, v117
	v_add_f32_e32 v107, v107, v108
	v_lshlrev_b32_e32 v108, 16, v202
	v_and_b32_e32 v109, 0xffff0000, v202
	v_lshlrev_b32_e32 v110, 16, v203
	v_and_b32_e32 v111, 0xffff0000, v203
	v_pk_mul_f32 v[104:105], v[104:105], v[116:117] op_sel_hi:[1,0]
	v_pk_mul_f32 v[102:103], v[102:103], v[116:117] op_sel_hi:[1,0]
	v_pk_fma_f32 v[104:105], v[132:133], v[104:105], v[110:111]
	v_pk_fma_f32 v[102:103], v[130:131], v[102:103], v[108:109]
	v_cndmask_b32_e32 v109, v105, v134, vcc
	v_cndmask_b32_e32 v111, v103, v134, vcc
	v_cndmask_b32_e32 v108, v104, v134, vcc
	v_cndmask_b32_e32 v110, v102, v134, vcc
	v_mul_f32_e32 v102, v111, v111
	v_mul_f32_e32 v103, v109, v109
	v_fmac_f32_e32 v102, v110, v110
	v_fmac_f32_e32 v103, v108, v108
	v_add_f32_e32 v107, v115, v107
	v_add_f32_e32 v102, v102, v103
	v_add_f32_e32 v107, v102, v107
	v_lshlrev_b32_e32 v102, 16, v200
	v_and_b32_e32 v103, 0xffff0000, v200
	v_lshlrev_b32_e32 v104, 16, v201
	v_and_b32_e32 v105, 0xffff0000, v201
	v_pk_mul_f32 v[100:101], v[100:101], v[116:117] op_sel_hi:[1,0]
	v_pk_mul_f32 v[98:99], v[98:99], v[116:117] op_sel_hi:[1,0]
	v_pk_fma_f32 v[100:101], v[128:129], v[100:101], v[104:105]
	v_pk_fma_f32 v[98:99], v[126:127], v[98:99], v[102:103]
	v_cndmask_b32_e32 v103, v101, v134, vcc
	v_cndmask_b32_e32 v105, v99, v134, vcc
	v_cndmask_b32_e32 v102, v100, v134, vcc
	v_cndmask_b32_e32 v104, v98, v134, vcc
	v_mul_f32_e32 v98, v105, v105
	v_mul_f32_e32 v99, v103, v103
	v_fmac_f32_e32 v98, v104, v104
	v_fmac_f32_e32 v99, v102, v102
	v_add_f32_e32 v98, v98, v99
	v_add_f32_e32 v98, v98, v107
	ds_bpermute_b32 v99, v1, v98
	v_cvt_pk_bf16_f32 v107, v117, v118
	v_mov_b32_e32 v242, v106
	v_mov_b32_e32 v243, v107
	s_nop 1
	v_permlane32_swap_b32_e32 v240, v242
	v_permlane32_swap_b32_e32 v241, v243
	s_nop 0
	v_permlane16_swap_b32_e32 v240, v242
	v_permlane16_swap_b32_e32 v241, v243
	v_lshl_add_u64 v[236:237], v[112:113], 0, v[238:239]
	global_store_dwordx4 v[236:237], v[240:243], off
	v_cvt_pk_bf16_f32 v100, v110, v111
	v_cvt_pk_bf16_f32 v101, v108, v109
	s_waitcnt lgkmcnt(0)
	v_add_f32_e32 v98, v98, v99
	ds_bpermute_b32 v99, v233, v98
	v_mov_b32_e32 v244, v100
	v_mov_b32_e32 v245, v101
	v_cvt_pk_bf16_f32 v100, v104, v105
	v_cvt_pk_bf16_f32 v101, v102, v103
	v_mov_b32_e32 v246, v100
	v_mov_b32_e32 v247, v101
	s_nop 1
	v_permlane32_swap_b32_e32 v244, v246
	v_permlane32_swap_b32_e32 v245, v247
	s_nop 0
	v_permlane16_swap_b32_e32 v244, v246
	v_permlane16_swap_b32_e32 v245, v247
	v_lshl_add_u64 v[236:237], v[112:113], 0, v[238:239]
	global_store_dwordx4 v[236:237], v[244:247], off offset:256
	s_and_saveexec_b64 s[2:3], s[4:5]
	s_cbranch_execz .LBB0_510
	v_lshl_add_u32 v100, v114, 4, s34
	s_waitcnt lgkmcnt(0)
	v_add_f32_e32 v98, v98, v99
	ds_write_b32 v100, v98 offset:16384
.LBB0_510:
	s_or_b64 exec, exec, s[2:3]
	ds_read_b32 v100, v146 offset:8320
	v_or_b32_e32 v98, 32, v222
	v_add_u32_e32 v102, s33, v98
	v_ashrrev_i32_e32 v103, 31, v102
	v_lshlrev_b64 v[102:103], 11, v[102:103]
	v_lshlrev_b32_e32 v104, 16, v198
	v_and_b32_e32 v105, 0xffff0000, v198
	v_lshlrev_b32_e32 v106, 16, v199
	v_and_b32_e32 v107, 0xffff0000, v199
	s_waitcnt lgkmcnt(0)
	v_pk_mul_f32 v[96:97], v[96:97], v[100:101] op_sel_hi:[1,0]
	v_pk_mul_f32 v[94:95], v[94:95], v[100:101] op_sel_hi:[1,0]
	v_pk_fma_f32 v[96:97], v[144:145], v[96:97], v[106:107]
	v_pk_fma_f32 v[104:105], v[142:143], v[94:95], v[104:105]
	v_mov_b32_e32 v94, 0x7fc00000
	v_lshl_add_u64 v[102:103], s[0:1], 0, v[102:103]
	v_cndmask_b32_e32 v95, v96, v94, vcc
	v_cndmask_b32_e32 v99, v97, v94, vcc
	v_cndmask_b32_e32 v101, v104, v94, vcc
	v_cndmask_b32_e32 v104, v105, v94, vcc
	v_cvt_pk_bf16_f32 v96, v101, v104
	v_cvt_pk_bf16_f32 v97, v95, v99
	v_lshl_add_u64 v[102:103], v[150:151], 1, v[102:103]
	v_mov_b32_e32 v240, v96
	v_mov_b32_e32 v241, v97
	v_mul_f32_e32 v96, v104, v104
	v_mul_f32_e32 v97, v99, v99
	v_fmac_f32_e32 v96, v101, v101
	v_fmac_f32_e32 v97, v95, v95
	v_add_f32_e32 v95, v96, v97
	v_lshlrev_b32_e32 v96, 16, v196
	v_and_b32_e32 v97, 0xffff0000, v196
	v_pk_mul_f32 v[90:91], v[90:91], v[100:101] op_sel_hi:[1,0]
	v_lshlrev_b32_e32 v104, 16, v197
	v_and_b32_e32 v105, 0xffff0000, v197
	v_pk_mul_f32 v[92:93], v[92:93], v[100:101] op_sel_hi:[1,0]
	v_pk_fma_f32 v[90:91], v[138:139], v[90:91], v[96:97]
	v_pk_fma_f32 v[92:93], v[140:141], v[92:93], v[104:105]
	v_cndmask_b32_e32 v91, v91, v94, vcc
	v_cndmask_b32_e32 v99, v92, v94, vcc
	v_cndmask_b32_e32 v101, v93, v94, vcc
	v_cndmask_b32_e32 v92, v90, v94, vcc
	v_cvt_pk_bf16_f32 v90, v92, v91
	v_mul_f32_e32 v91, v91, v91
	v_fmac_f32_e32 v91, v92, v92
	v_mul_f32_e32 v92, v101, v101
	v_fmac_f32_e32 v92, v99, v99
	v_add_f32_e32 v91, v91, v92
	v_lshlrev_b32_e32 v92, 16, v194
	v_and_b32_e32 v93, 0xffff0000, v194
	v_lshlrev_b32_e32 v96, 16, v195
	v_and_b32_e32 v97, 0xffff0000, v195
	v_pk_mul_f32 v[88:89], v[88:89], v[100:101] op_sel_hi:[1,0]
	v_pk_mul_f32 v[86:87], v[86:87], v[100:101] op_sel_hi:[1,0]
	v_pk_fma_f32 v[88:89], v[132:133], v[88:89], v[96:97]
	v_pk_fma_f32 v[86:87], v[130:131], v[86:87], v[92:93]
	v_cndmask_b32_e32 v93, v89, v94, vcc
	v_cndmask_b32_e32 v96, v87, v94, vcc
	v_add_f32_e32 v91, v95, v91
	v_cndmask_b32_e32 v92, v88, v94, vcc
	v_cndmask_b32_e32 v95, v86, v94, vcc
	v_mul_f32_e32 v86, v96, v96
	v_mul_f32_e32 v87, v93, v93
	v_fmac_f32_e32 v86, v95, v95
	v_fmac_f32_e32 v87, v92, v92
	v_add_f32_e32 v86, v86, v87
	v_add_f32_e32 v91, v86, v91
	v_lshlrev_b32_e32 v86, 16, v192
	v_and_b32_e32 v87, 0xffff0000, v192
	v_lshlrev_b32_e32 v88, 16, v193
	v_and_b32_e32 v89, 0xffff0000, v193
	v_pk_mul_f32 v[84:85], v[84:85], v[100:101] op_sel_hi:[1,0]
	v_pk_mul_f32 v[82:83], v[82:83], v[100:101] op_sel_hi:[1,0]
	v_pk_fma_f32 v[84:85], v[128:129], v[84:85], v[88:89]
	v_pk_fma_f32 v[82:83], v[126:127], v[82:83], v[86:87]
	v_cndmask_b32_e32 v87, v85, v94, vcc
	v_cndmask_b32_e32 v89, v83, v94, vcc
	v_cndmask_b32_e32 v86, v84, v94, vcc
	v_cndmask_b32_e32 v88, v82, v94, vcc
	v_mul_f32_e32 v82, v89, v89
	v_mul_f32_e32 v83, v87, v87
	v_fmac_f32_e32 v82, v88, v88
	v_fmac_f32_e32 v83, v86, v86
	v_add_f32_e32 v82, v82, v83
	v_add_f32_e32 v82, v82, v91
	ds_bpermute_b32 v83, v1, v82
	v_cvt_pk_bf16_f32 v91, v99, v101
	v_mov_b32_e32 v242, v90
	v_mov_b32_e32 v243, v91
	s_nop 1
	v_permlane32_swap_b32_e32 v240, v242
	v_permlane32_swap_b32_e32 v241, v243
	s_nop 0
	v_permlane16_swap_b32_e32 v240, v242
	v_permlane16_swap_b32_e32 v241, v243
	v_lshl_add_u64 v[236:237], v[102:103], 0, v[238:239]
	global_store_dwordx4 v[236:237], v[240:243], off
	v_cvt_pk_bf16_f32 v84, v95, v96
	v_cvt_pk_bf16_f32 v85, v92, v93
	s_waitcnt lgkmcnt(0)
	v_add_f32_e32 v82, v82, v83
	ds_bpermute_b32 v83, v233, v82
	v_mov_b32_e32 v244, v84
	v_mov_b32_e32 v245, v85
	v_cvt_pk_bf16_f32 v84, v88, v89
	v_cvt_pk_bf16_f32 v85, v86, v87
	v_mov_b32_e32 v246, v84
	v_mov_b32_e32 v247, v85
	s_nop 1
	v_permlane32_swap_b32_e32 v244, v246
	v_permlane32_swap_b32_e32 v245, v247
	s_nop 0
	v_permlane16_swap_b32_e32 v244, v246
	v_permlane16_swap_b32_e32 v245, v247
	v_lshl_add_u64 v[236:237], v[102:103], 0, v[238:239]
	global_store_dwordx4 v[236:237], v[244:247], off offset:256
	s_and_saveexec_b64 s[2:3], s[4:5]
	s_cbranch_execz .LBB0_512
	v_lshl_add_u32 v84, v98, 4, s34
	s_waitcnt lgkmcnt(0)
	v_add_f32_e32 v82, v82, v83
	ds_write_b32 v84, v82 offset:16384
.LBB0_512:
	s_or_b64 exec, exec, s[2:3]
	ds_read_b32 v84, v146 offset:8384
	v_or_b32_e32 v82, 48, v222
	v_add_u32_e32 v86, s33, v82
	v_ashrrev_i32_e32 v87, 31, v86
	v_lshlrev_b32_e32 v90, 16, v191
	v_and_b32_e32 v91, 0xffff0000, v191
	s_waitcnt lgkmcnt(0)
	v_pk_mul_f32 v[80:81], v[80:81], v[84:85] op_sel_hi:[1,0]
	v_lshlrev_b64 v[86:87], 11, v[86:87]
	v_lshlrev_b32_e32 v88, 16, v190
	v_and_b32_e32 v89, 0xffff0000, v190
	v_pk_mul_f32 v[78:79], v[78:79], v[84:85] op_sel_hi:[1,0]
	v_pk_fma_f32 v[80:81], v[144:145], v[80:81], v[90:91]
	v_pk_fma_f32 v[78:79], v[142:143], v[78:79], v[88:89]
	v_cndmask_b32_e32 v83, v80, v94, vcc
	v_cndmask_b32_e32 v85, v81, v94, vcc
	v_lshl_add_u64 v[80:81], s[0:1], 0, v[86:87]
	v_cndmask_b32_e32 v88, v78, v94, vcc
	v_cndmask_b32_e32 v89, v79, v94, vcc
	v_cvt_pk_bf16_f32 v78, v88, v89
	v_cvt_pk_bf16_f32 v79, v83, v85
	v_lshl_add_u64 v[80:81], v[150:151], 1, v[80:81]
	v_mov_b32_e32 v240, v78
	v_mov_b32_e32 v241, v79
	v_mul_f32_e32 v78, v89, v89
	v_mul_f32_e32 v79, v85, v85
	v_fmac_f32_e32 v78, v88, v88
	v_fmac_f32_e32 v79, v83, v83
	v_add_f32_e32 v83, v78, v79
	v_lshlrev_b32_e32 v78, 16, v188
	v_and_b32_e32 v79, 0xffff0000, v188
	v_pk_mul_f32 v[74:75], v[74:75], v[84:85] op_sel_hi:[1,0]
	v_lshlrev_b32_e32 v86, 16, v189
	v_and_b32_e32 v87, 0xffff0000, v189
	v_pk_mul_f32 v[76:77], v[76:77], v[84:85] op_sel_hi:[1,0]
	v_pk_fma_f32 v[74:75], v[138:139], v[74:75], v[78:79]
	v_pk_fma_f32 v[76:77], v[140:141], v[76:77], v[86:87]
	v_cndmask_b32_e32 v75, v75, v94, vcc
	v_cndmask_b32_e32 v85, v76, v94, vcc
	v_cndmask_b32_e32 v86, v77, v94, vcc
	v_cndmask_b32_e32 v76, v74, v94, vcc
	v_cvt_pk_bf16_f32 v74, v76, v75
	v_mul_f32_e32 v75, v75, v75
	v_fmac_f32_e32 v75, v76, v76
	v_mul_f32_e32 v76, v86, v86
	v_fmac_f32_e32 v76, v85, v85
	v_add_f32_e32 v75, v75, v76
	v_lshlrev_b32_e32 v76, 16, v186
	v_and_b32_e32 v77, 0xffff0000, v186
	v_lshlrev_b32_e32 v78, 16, v187
	v_and_b32_e32 v79, 0xffff0000, v187
	v_pk_mul_f32 v[72:73], v[72:73], v[84:85] op_sel_hi:[1,0]
	v_pk_mul_f32 v[70:71], v[70:71], v[84:85] op_sel_hi:[1,0]
	v_pk_fma_f32 v[72:73], v[132:133], v[72:73], v[78:79]
	v_pk_fma_f32 v[70:71], v[130:131], v[70:71], v[76:77]
	v_cndmask_b32_e32 v77, v73, v94, vcc
	v_cndmask_b32_e32 v79, v71, v94, vcc
	v_cndmask_b32_e32 v76, v72, v94, vcc
	v_cndmask_b32_e32 v78, v70, v94, vcc
	v_mul_f32_e32 v70, v79, v79
	v_mul_f32_e32 v71, v77, v77
	v_fmac_f32_e32 v70, v78, v78
	v_fmac_f32_e32 v71, v76, v76
	v_add_f32_e32 v75, v83, v75
	v_add_f32_e32 v70, v70, v71
	v_add_f32_e32 v75, v70, v75
	v_lshlrev_b32_e32 v70, 16, v184
	v_and_b32_e32 v71, 0xffff0000, v184
	v_lshlrev_b32_e32 v72, 16, v185
	v_and_b32_e32 v73, 0xffff0000, v185
	v_pk_mul_f32 v[68:69], v[68:69], v[84:85] op_sel_hi:[1,0]
	v_pk_mul_f32 v[66:67], v[66:67], v[84:85] op_sel_hi:[1,0]
	v_pk_fma_f32 v[68:69], v[128:129], v[68:69], v[72:73]
	v_pk_fma_f32 v[66:67], v[126:127], v[66:67], v[70:71]
	v_cndmask_b32_e32 v71, v69, v94, vcc
	v_cndmask_b32_e32 v73, v67, v94, vcc
	v_cndmask_b32_e32 v70, v68, v94, vcc
	v_cndmask_b32_e32 v72, v66, v94, vcc
	v_mul_f32_e32 v66, v73, v73
	v_mul_f32_e32 v67, v71, v71
	v_fmac_f32_e32 v66, v72, v72
	v_fmac_f32_e32 v67, v70, v70
	v_add_f32_e32 v66, v66, v67
	v_add_f32_e32 v66, v66, v75
	ds_bpermute_b32 v67, v1, v66
	v_cvt_pk_bf16_f32 v75, v85, v86
	v_mov_b32_e32 v242, v74
	v_mov_b32_e32 v243, v75
	s_nop 1
	v_permlane32_swap_b32_e32 v240, v242
	v_permlane32_swap_b32_e32 v241, v243
	s_nop 0
	v_permlane16_swap_b32_e32 v240, v242
	v_permlane16_swap_b32_e32 v241, v243
	v_lshl_add_u64 v[236:237], v[80:81], 0, v[238:239]
	global_store_dwordx4 v[236:237], v[240:243], off
	v_cvt_pk_bf16_f32 v68, v78, v79
	v_cvt_pk_bf16_f32 v69, v76, v77
	s_waitcnt lgkmcnt(0)
	v_add_f32_e32 v66, v66, v67
	ds_bpermute_b32 v67, v233, v66
	v_mov_b32_e32 v244, v68
	v_mov_b32_e32 v245, v69
	v_cvt_pk_bf16_f32 v68, v72, v73
	v_cvt_pk_bf16_f32 v69, v70, v71
	v_mov_b32_e32 v246, v68
	v_mov_b32_e32 v247, v69
	s_nop 1
	v_permlane32_swap_b32_e32 v244, v246
	v_permlane32_swap_b32_e32 v245, v247
	s_nop 0
	v_permlane16_swap_b32_e32 v244, v246
	v_permlane16_swap_b32_e32 v245, v247
	v_lshl_add_u64 v[236:237], v[80:81], 0, v[238:239]
	global_store_dwordx4 v[236:237], v[244:247], off offset:256
	s_and_saveexec_b64 s[2:3], s[4:5]
	s_cbranch_execz .LBB0_514
	v_lshl_add_u32 v68, v82, 4, s34
	s_waitcnt lgkmcnt(0)
	v_add_f32_e32 v66, v66, v67
	ds_write_b32 v68, v66 offset:16384
.LBB0_514:
	s_or_b64 exec, exec, s[2:3]
	s_waitcnt lgkmcnt(0)
	v_add_u32_e32 v67, s30, v217
	v_lshl_add_u32 v67, v67, 2, 0
	ds_read_b32 v68, v67 offset:8704
	s_add_i32 s2, s30, 0x80
	v_or_b32_e32 v66, s2, v217
	v_add_u32_e32 v70, s33, v66
	v_ashrrev_i32_e32 v71, 31, v70
	v_lshlrev_b64 v[70:71], 11, v[70:71]
	v_lshlrev_b32_e32 v72, 16, v182
	v_and_b32_e32 v73, 0xffff0000, v182
	v_lshlrev_b32_e32 v74, 16, v183
	v_and_b32_e32 v75, 0xffff0000, v183
	s_waitcnt lgkmcnt(0)
	v_pk_mul_f32 v[64:65], v[64:65], v[68:69] op_sel_hi:[1,0]
	v_pk_mul_f32 v[62:63], v[62:63], v[68:69] op_sel_hi:[1,0]
	v_pk_fma_f32 v[64:65], v[144:145], v[64:65], v[74:75]
	v_pk_fma_f32 v[72:73], v[142:143], v[62:63], v[72:73]
	v_mov_b32_e32 v62, 0x7fc00000
	v_lshl_add_u64 v[70:71], s[0:1], 0, v[70:71]
	v_cndmask_b32_e32 v63, v64, v62, vcc
	v_cndmask_b32_e32 v69, v65, v62, vcc
	v_cndmask_b32_e32 v72, v72, v62, vcc
	v_cndmask_b32_e32 v73, v73, v62, vcc
	v_cvt_pk_bf16_f32 v64, v72, v73
	v_cvt_pk_bf16_f32 v65, v63, v69
	v_lshl_add_u64 v[70:71], v[150:151], 1, v[70:71]
	v_mov_b32_e32 v240, v64
	v_mov_b32_e32 v241, v65
	v_mul_f32_e32 v64, v73, v73
	v_mul_f32_e32 v65, v69, v69
	v_fmac_f32_e32 v64, v72, v72
	v_fmac_f32_e32 v65, v63, v63
	v_add_f32_e32 v63, v64, v65
	v_lshlrev_b32_e32 v64, 16, v180
	v_and_b32_e32 v65, 0xffff0000, v180
	v_pk_mul_f32 v[58:59], v[58:59], v[68:69] op_sel_hi:[1,0]
	v_lshlrev_b32_e32 v72, 16, v181
	v_and_b32_e32 v73, 0xffff0000, v181
	v_pk_mul_f32 v[60:61], v[60:61], v[68:69] op_sel_hi:[1,0]
	v_pk_fma_f32 v[58:59], v[138:139], v[58:59], v[64:65]
	v_pk_fma_f32 v[60:61], v[140:141], v[60:61], v[72:73]
	v_cndmask_b32_e32 v59, v59, v62, vcc
	v_cndmask_b32_e32 v69, v60, v62, vcc
	v_cndmask_b32_e32 v72, v61, v62, vcc
	v_cndmask_b32_e32 v60, v58, v62, vcc
	v_cvt_pk_bf16_f32 v58, v60, v59
	v_mul_f32_e32 v59, v59, v59
	v_fmac_f32_e32 v59, v60, v60
	v_mul_f32_e32 v60, v72, v72
	v_fmac_f32_e32 v60, v69, v69
	v_add_f32_e32 v59, v59, v60
	v_lshlrev_b32_e32 v60, 16, v178
	v_and_b32_e32 v61, 0xffff0000, v178
	v_lshlrev_b32_e32 v64, 16, v179
	v_and_b32_e32 v65, 0xffff0000, v179
	v_pk_mul_f32 v[56:57], v[56:57], v[68:69] op_sel_hi:[1,0]
	v_pk_mul_f32 v[54:55], v[54:55], v[68:69] op_sel_hi:[1,0]
	v_pk_fma_f32 v[56:57], v[132:133], v[56:57], v[64:65]
	v_pk_fma_f32 v[54:55], v[130:131], v[54:55], v[60:61]
	v_cndmask_b32_e32 v61, v57, v62, vcc
	v_cndmask_b32_e32 v64, v55, v62, vcc
	v_add_f32_e32 v59, v63, v59
	v_cndmask_b32_e32 v60, v56, v62, vcc
	v_cndmask_b32_e32 v63, v54, v62, vcc
	v_mul_f32_e32 v54, v64, v64
	v_mul_f32_e32 v55, v61, v61
	v_fmac_f32_e32 v54, v63, v63
	v_fmac_f32_e32 v55, v60, v60
	v_add_f32_e32 v54, v54, v55
	v_add_f32_e32 v59, v54, v59
	v_lshlrev_b32_e32 v54, 16, v176
	v_and_b32_e32 v55, 0xffff0000, v176
	v_lshlrev_b32_e32 v56, 16, v177
	v_and_b32_e32 v57, 0xffff0000, v177
	v_pk_mul_f32 v[52:53], v[52:53], v[68:69] op_sel_hi:[1,0]
	v_pk_mul_f32 v[50:51], v[50:51], v[68:69] op_sel_hi:[1,0]
	v_pk_fma_f32 v[52:53], v[128:129], v[52:53], v[56:57]
	v_pk_fma_f32 v[50:51], v[126:127], v[50:51], v[54:55]
	v_cndmask_b32_e32 v55, v53, v62, vcc
	v_cndmask_b32_e32 v57, v51, v62, vcc
	v_cndmask_b32_e32 v54, v52, v62, vcc
	v_cndmask_b32_e32 v56, v50, v62, vcc
	v_mul_f32_e32 v50, v57, v57
	v_mul_f32_e32 v51, v55, v55
	v_fmac_f32_e32 v50, v56, v56
	v_fmac_f32_e32 v51, v54, v54
	v_add_f32_e32 v50, v50, v51
	v_add_f32_e32 v50, v50, v59
	ds_bpermute_b32 v51, v1, v50
	v_cvt_pk_bf16_f32 v59, v69, v72
	v_mov_b32_e32 v242, v58
	v_mov_b32_e32 v243, v59
	s_nop 1
	v_permlane32_swap_b32_e32 v240, v242
	v_permlane32_swap_b32_e32 v241, v243
	s_nop 0
	v_permlane16_swap_b32_e32 v240, v242
	v_permlane16_swap_b32_e32 v241, v243
	v_lshl_add_u64 v[236:237], v[70:71], 0, v[238:239]
	global_store_dwordx4 v[236:237], v[240:243], off
	v_cvt_pk_bf16_f32 v52, v63, v64
	v_cvt_pk_bf16_f32 v53, v60, v61
	s_waitcnt lgkmcnt(0)
	v_add_f32_e32 v50, v50, v51
	ds_bpermute_b32 v51, v233, v50
	v_mov_b32_e32 v244, v52
	v_mov_b32_e32 v245, v53
	v_cvt_pk_bf16_f32 v52, v56, v57
	v_cvt_pk_bf16_f32 v53, v54, v55
	v_mov_b32_e32 v246, v52
	v_mov_b32_e32 v247, v53
	s_nop 1
	v_permlane32_swap_b32_e32 v244, v246
	v_permlane32_swap_b32_e32 v245, v247
	s_nop 0
	v_permlane16_swap_b32_e32 v244, v246
	v_permlane16_swap_b32_e32 v245, v247
	v_lshl_add_u64 v[236:237], v[70:71], 0, v[238:239]
	global_store_dwordx4 v[236:237], v[244:247], off offset:256
	s_and_saveexec_b64 s[2:3], s[4:5]
	s_cbranch_execz .LBB0_516
	v_lshl_add_u32 v52, v66, 4, s34
	s_waitcnt lgkmcnt(0)
	v_add_f32_e32 v50, v50, v51
	ds_write_b32 v52, v50 offset:16384
.LBB0_516:
	s_or_b64 exec, exec, s[2:3]
	ds_read_b32 v52, v67 offset:8768
	v_or_b32_e32 v50, 16, v66
	v_add_u32_e32 v54, s33, v50
	v_ashrrev_i32_e32 v55, 31, v54
	v_lshlrev_b32_e32 v58, 16, v175
	v_and_b32_e32 v59, 0xffff0000, v175
	s_waitcnt lgkmcnt(0)
	v_pk_mul_f32 v[48:49], v[48:49], v[52:53] op_sel_hi:[1,0]
	v_lshlrev_b64 v[54:55], 11, v[54:55]
	v_lshlrev_b32_e32 v56, 16, v174
	v_and_b32_e32 v57, 0xffff0000, v174
	v_pk_mul_f32 v[46:47], v[46:47], v[52:53] op_sel_hi:[1,0]
	v_pk_fma_f32 v[48:49], v[144:145], v[48:49], v[58:59]
	v_pk_fma_f32 v[46:47], v[142:143], v[46:47], v[56:57]
	v_cndmask_b32_e32 v51, v48, v62, vcc
	v_cndmask_b32_e32 v53, v49, v62, vcc
	v_lshl_add_u64 v[48:49], s[0:1], 0, v[54:55]
	v_cndmask_b32_e32 v56, v46, v62, vcc
	v_cndmask_b32_e32 v57, v47, v62, vcc
	v_cvt_pk_bf16_f32 v46, v56, v57
	v_cvt_pk_bf16_f32 v47, v51, v53
	v_lshl_add_u64 v[48:49], v[150:151], 1, v[48:49]
	v_mov_b32_e32 v240, v46
	v_mov_b32_e32 v241, v47
	v_mul_f32_e32 v46, v57, v57
	v_mul_f32_e32 v47, v53, v53
	v_fmac_f32_e32 v46, v56, v56
	v_fmac_f32_e32 v47, v51, v51
	v_add_f32_e32 v51, v46, v47
	v_lshlrev_b32_e32 v46, 16, v172
	v_and_b32_e32 v47, 0xffff0000, v172
	v_pk_mul_f32 v[42:43], v[42:43], v[52:53] op_sel_hi:[1,0]
	v_lshlrev_b32_e32 v54, 16, v173
	v_and_b32_e32 v55, 0xffff0000, v173
	v_pk_mul_f32 v[44:45], v[44:45], v[52:53] op_sel_hi:[1,0]
	v_pk_fma_f32 v[42:43], v[138:139], v[42:43], v[46:47]
	v_pk_fma_f32 v[44:45], v[140:141], v[44:45], v[54:55]
	v_cndmask_b32_e32 v43, v43, v62, vcc
	v_cndmask_b32_e32 v53, v44, v62, vcc
	v_cndmask_b32_e32 v54, v45, v62, vcc
	v_cndmask_b32_e32 v44, v42, v62, vcc
	v_cvt_pk_bf16_f32 v42, v44, v43
	v_mul_f32_e32 v43, v43, v43
	v_fmac_f32_e32 v43, v44, v44
	v_mul_f32_e32 v44, v54, v54
	v_fmac_f32_e32 v44, v53, v53
	v_add_f32_e32 v43, v43, v44
	v_lshlrev_b32_e32 v44, 16, v170
	v_and_b32_e32 v45, 0xffff0000, v170
	v_lshlrev_b32_e32 v46, 16, v171
	v_and_b32_e32 v47, 0xffff0000, v171
	v_pk_mul_f32 v[40:41], v[40:41], v[52:53] op_sel_hi:[1,0]
	v_pk_mul_f32 v[38:39], v[38:39], v[52:53] op_sel_hi:[1,0]
	v_pk_fma_f32 v[40:41], v[132:133], v[40:41], v[46:47]
	v_pk_fma_f32 v[38:39], v[130:131], v[38:39], v[44:45]
	v_cndmask_b32_e32 v45, v41, v62, vcc
	v_cndmask_b32_e32 v47, v39, v62, vcc
	v_cndmask_b32_e32 v44, v40, v62, vcc
	v_cndmask_b32_e32 v46, v38, v62, vcc
	v_mul_f32_e32 v38, v47, v47
	v_mul_f32_e32 v39, v45, v45
	v_fmac_f32_e32 v38, v46, v46
	v_fmac_f32_e32 v39, v44, v44
	v_add_f32_e32 v43, v51, v43
	v_add_f32_e32 v38, v38, v39
	v_add_f32_e32 v43, v38, v43
	v_lshlrev_b32_e32 v38, 16, v168
	v_and_b32_e32 v39, 0xffff0000, v168
	v_lshlrev_b32_e32 v40, 16, v169
	v_and_b32_e32 v41, 0xffff0000, v169
	v_pk_mul_f32 v[36:37], v[36:37], v[52:53] op_sel_hi:[1,0]
	v_pk_mul_f32 v[34:35], v[34:35], v[52:53] op_sel_hi:[1,0]
	v_pk_fma_f32 v[36:37], v[128:129], v[36:37], v[40:41]
	v_pk_fma_f32 v[34:35], v[126:127], v[34:35], v[38:39]
	v_cndmask_b32_e32 v39, v37, v62, vcc
	v_cndmask_b32_e32 v41, v35, v62, vcc
	v_cndmask_b32_e32 v38, v36, v62, vcc
	v_cndmask_b32_e32 v40, v34, v62, vcc
	v_mul_f32_e32 v34, v41, v41
	v_mul_f32_e32 v35, v39, v39
	v_fmac_f32_e32 v34, v40, v40
	v_fmac_f32_e32 v35, v38, v38
	v_add_f32_e32 v34, v34, v35
	v_add_f32_e32 v34, v34, v43
	ds_bpermute_b32 v35, v1, v34
	v_cvt_pk_bf16_f32 v43, v53, v54
	v_mov_b32_e32 v242, v42
	v_mov_b32_e32 v243, v43
	s_nop 1
	v_permlane32_swap_b32_e32 v240, v242
	v_permlane32_swap_b32_e32 v241, v243
	s_nop 0
	v_permlane16_swap_b32_e32 v240, v242
	v_permlane16_swap_b32_e32 v241, v243
	v_lshl_add_u64 v[236:237], v[48:49], 0, v[238:239]
	global_store_dwordx4 v[236:237], v[240:243], off
	v_cvt_pk_bf16_f32 v36, v46, v47
	v_cvt_pk_bf16_f32 v37, v44, v45
	s_waitcnt lgkmcnt(0)
	v_add_f32_e32 v34, v34, v35
	ds_bpermute_b32 v35, v233, v34
	v_mov_b32_e32 v244, v36
	v_mov_b32_e32 v245, v37
	v_cvt_pk_bf16_f32 v36, v40, v41
	v_cvt_pk_bf16_f32 v37, v38, v39
	v_mov_b32_e32 v246, v36
	v_mov_b32_e32 v247, v37
	s_nop 1
	v_permlane32_swap_b32_e32 v244, v246
	v_permlane32_swap_b32_e32 v245, v247
	s_nop 0
	v_permlane16_swap_b32_e32 v244, v246
	v_permlane16_swap_b32_e32 v245, v247
	v_lshl_add_u64 v[236:237], v[48:49], 0, v[238:239]
	global_store_dwordx4 v[236:237], v[244:247], off offset:256
	s_and_saveexec_b64 s[2:3], s[4:5]
	s_cbranch_execz .LBB0_518
	v_lshl_add_u32 v36, v50, 4, s34
	s_waitcnt lgkmcnt(0)
	v_add_f32_e32 v34, v34, v35
	ds_write_b32 v36, v34 offset:16384
.LBB0_518:
	s_or_b64 exec, exec, s[2:3]
	ds_read_b32 v36, v146 offset:8832
	v_or_b32_e32 v34, 32, v66
	v_add_u32_e32 v38, s33, v34
	v_ashrrev_i32_e32 v39, 31, v38
	v_lshlrev_b64 v[38:39], 11, v[38:39]
	v_lshlrev_b32_e32 v40, 16, v166
	v_and_b32_e32 v41, 0xffff0000, v166
	v_lshlrev_b32_e32 v42, 16, v167
	v_and_b32_e32 v43, 0xffff0000, v167
	s_waitcnt lgkmcnt(0)
	v_pk_mul_f32 v[32:33], v[32:33], v[36:37] op_sel_hi:[1,0]
	v_pk_mul_f32 v[30:31], v[30:31], v[36:37] op_sel_hi:[1,0]
	v_pk_fma_f32 v[32:33], v[144:145], v[32:33], v[42:43]
	v_pk_fma_f32 v[40:41], v[142:143], v[30:31], v[40:41]
	v_mov_b32_e32 v30, 0x7fc00000
	v_lshl_add_u64 v[38:39], s[0:1], 0, v[38:39]
	v_cndmask_b32_e32 v31, v32, v30, vcc
	v_cndmask_b32_e32 v35, v33, v30, vcc
	v_cndmask_b32_e32 v37, v40, v30, vcc
	v_cndmask_b32_e32 v40, v41, v30, vcc
	v_cvt_pk_bf16_f32 v32, v37, v40
	v_cvt_pk_bf16_f32 v33, v31, v35
	v_lshl_add_u64 v[38:39], v[150:151], 1, v[38:39]
	v_mov_b32_e32 v240, v32
	v_mov_b32_e32 v241, v33
	v_mul_f32_e32 v32, v40, v40
	v_mul_f32_e32 v33, v35, v35
	v_fmac_f32_e32 v32, v37, v37
	v_fmac_f32_e32 v33, v31, v31
	v_add_f32_e32 v31, v32, v33
	v_lshlrev_b32_e32 v32, 16, v164
	v_and_b32_e32 v33, 0xffff0000, v164
	v_pk_mul_f32 v[26:27], v[26:27], v[36:37] op_sel_hi:[1,0]
	v_lshlrev_b32_e32 v40, 16, v165
	v_and_b32_e32 v41, 0xffff0000, v165
	v_pk_mul_f32 v[28:29], v[28:29], v[36:37] op_sel_hi:[1,0]
	v_pk_fma_f32 v[26:27], v[138:139], v[26:27], v[32:33]
	v_pk_fma_f32 v[28:29], v[140:141], v[28:29], v[40:41]
	v_cndmask_b32_e32 v27, v27, v30, vcc
	v_cndmask_b32_e32 v35, v28, v30, vcc
	v_cndmask_b32_e32 v37, v29, v30, vcc
	v_cndmask_b32_e32 v28, v26, v30, vcc
	v_cvt_pk_bf16_f32 v26, v28, v27
	v_mul_f32_e32 v27, v27, v27
	v_fmac_f32_e32 v27, v28, v28
	v_mul_f32_e32 v28, v37, v37
	v_fmac_f32_e32 v28, v35, v35
	v_add_f32_e32 v27, v27, v28
	v_lshlrev_b32_e32 v28, 16, v162
	v_and_b32_e32 v29, 0xffff0000, v162
	v_lshlrev_b32_e32 v32, 16, v163
	v_and_b32_e32 v33, 0xffff0000, v163
	v_pk_mul_f32 v[24:25], v[24:25], v[36:37] op_sel_hi:[1,0]
	v_pk_mul_f32 v[22:23], v[22:23], v[36:37] op_sel_hi:[1,0]
	v_pk_fma_f32 v[24:25], v[132:133], v[24:25], v[32:33]
	v_pk_fma_f32 v[22:23], v[130:131], v[22:23], v[28:29]
	v_cndmask_b32_e32 v29, v25, v30, vcc
	v_cndmask_b32_e32 v32, v23, v30, vcc
	v_add_f32_e32 v27, v31, v27
	v_cndmask_b32_e32 v28, v24, v30, vcc
	v_cndmask_b32_e32 v31, v22, v30, vcc
	v_mul_f32_e32 v22, v32, v32
	v_mul_f32_e32 v23, v29, v29
	v_fmac_f32_e32 v22, v31, v31
	v_fmac_f32_e32 v23, v28, v28
	v_add_f32_e32 v22, v22, v23
	v_add_f32_e32 v27, v22, v27
	v_lshlrev_b32_e32 v22, 16, v160
	v_and_b32_e32 v23, 0xffff0000, v160
	v_lshlrev_b32_e32 v24, 16, v161
	v_and_b32_e32 v25, 0xffff0000, v161
	v_pk_mul_f32 v[20:21], v[20:21], v[36:37] op_sel_hi:[1,0]
	v_pk_mul_f32 v[18:19], v[18:19], v[36:37] op_sel_hi:[1,0]
	v_pk_fma_f32 v[20:21], v[128:129], v[20:21], v[24:25]
	v_pk_fma_f32 v[18:19], v[126:127], v[18:19], v[22:23]
	v_cndmask_b32_e32 v23, v21, v30, vcc
	v_cndmask_b32_e32 v25, v19, v30, vcc
	v_cndmask_b32_e32 v22, v20, v30, vcc
	v_cndmask_b32_e32 v24, v18, v30, vcc
	v_mul_f32_e32 v18, v25, v25
	v_mul_f32_e32 v19, v23, v23
	v_fmac_f32_e32 v18, v24, v24
	v_fmac_f32_e32 v19, v22, v22
	v_add_f32_e32 v18, v18, v19
	v_add_f32_e32 v18, v18, v27
	ds_bpermute_b32 v19, v1, v18
	v_cvt_pk_bf16_f32 v27, v35, v37
	v_mov_b32_e32 v242, v26
	v_mov_b32_e32 v243, v27
	s_nop 1
	v_permlane32_swap_b32_e32 v240, v242
	v_permlane32_swap_b32_e32 v241, v243
	s_nop 0
	v_permlane16_swap_b32_e32 v240, v242
	v_permlane16_swap_b32_e32 v241, v243
	v_lshl_add_u64 v[236:237], v[38:39], 0, v[238:239]
	global_store_dwordx4 v[236:237], v[240:243], off
	v_cvt_pk_bf16_f32 v20, v31, v32
	v_cvt_pk_bf16_f32 v21, v28, v29
	s_waitcnt lgkmcnt(0)
	v_add_f32_e32 v18, v18, v19
	ds_bpermute_b32 v19, v233, v18
	v_mov_b32_e32 v244, v20
	v_mov_b32_e32 v245, v21
	v_cvt_pk_bf16_f32 v20, v24, v25
	v_cvt_pk_bf16_f32 v21, v22, v23
	v_mov_b32_e32 v246, v20
	v_mov_b32_e32 v247, v21
	s_nop 1
	v_permlane32_swap_b32_e32 v244, v246
	v_permlane32_swap_b32_e32 v245, v247
	s_nop 0
	v_permlane16_swap_b32_e32 v244, v246
	v_permlane16_swap_b32_e32 v245, v247
	v_lshl_add_u64 v[236:237], v[38:39], 0, v[238:239]
	global_store_dwordx4 v[236:237], v[244:247], off offset:256
	s_and_saveexec_b64 s[2:3], s[4:5]
	s_cbranch_execz .LBB0_520
	v_lshl_add_u32 v20, v34, 4, s34
	s_waitcnt lgkmcnt(0)
	v_add_f32_e32 v18, v18, v19
	ds_write_b32 v20, v18 offset:16384
.LBB0_520:
	s_or_b64 exec, exec, s[2:3]
	ds_read_b32 v20, v67 offset:8896
	v_or_b32_e32 v18, 48, v66
	v_add_u32_e32 v22, s33, v18
	v_ashrrev_i32_e32 v23, 31, v22
	v_lshlrev_b32_e32 v26, 16, v159
	v_and_b32_e32 v27, 0xffff0000, v159
	s_waitcnt lgkmcnt(0)
	v_pk_mul_f32 v[16:17], v[16:17], v[20:21] op_sel_hi:[1,0]
	v_lshlrev_b64 v[22:23], 11, v[22:23]
	v_lshlrev_b32_e32 v24, 16, v158
	v_and_b32_e32 v25, 0xffff0000, v158
	v_pk_mul_f32 v[14:15], v[14:15], v[20:21] op_sel_hi:[1,0]
	v_pk_fma_f32 v[16:17], v[144:145], v[16:17], v[26:27]
	v_pk_fma_f32 v[14:15], v[142:143], v[14:15], v[24:25]
	v_cndmask_b32_e32 v19, v16, v30, vcc
	v_cndmask_b32_e32 v21, v17, v30, vcc
	v_lshl_add_u64 v[16:17], s[0:1], 0, v[22:23]
	v_cndmask_b32_e32 v24, v14, v30, vcc
	v_cndmask_b32_e32 v25, v15, v30, vcc
	v_cvt_pk_bf16_f32 v14, v24, v25
	v_cvt_pk_bf16_f32 v15, v19, v21
	v_lshl_add_u64 v[16:17], v[150:151], 1, v[16:17]
	v_mov_b32_e32 v240, v14
	v_mov_b32_e32 v241, v15
	v_mul_f32_e32 v14, v25, v25
	v_mul_f32_e32 v15, v21, v21
	v_fmac_f32_e32 v14, v24, v24
	v_fmac_f32_e32 v15, v19, v19
	v_add_f32_e32 v19, v14, v15
	v_lshlrev_b32_e32 v14, 16, v156
	v_and_b32_e32 v15, 0xffff0000, v156
	v_pk_mul_f32 v[10:11], v[10:11], v[20:21] op_sel_hi:[1,0]
	v_lshlrev_b32_e32 v22, 16, v157
	v_and_b32_e32 v23, 0xffff0000, v157
	v_pk_mul_f32 v[12:13], v[12:13], v[20:21] op_sel_hi:[1,0]
	v_pk_fma_f32 v[10:11], v[138:139], v[10:11], v[14:15]
	v_pk_fma_f32 v[12:13], v[140:141], v[12:13], v[22:23]
	v_cndmask_b32_e32 v11, v11, v30, vcc
	v_cndmask_b32_e32 v21, v12, v30, vcc
	v_cndmask_b32_e32 v22, v13, v30, vcc
	v_cndmask_b32_e32 v12, v10, v30, vcc
	v_cvt_pk_bf16_f32 v10, v12, v11
	v_mul_f32_e32 v11, v11, v11
	v_fmac_f32_e32 v11, v12, v12
	v_mul_f32_e32 v12, v22, v22
	v_fmac_f32_e32 v12, v21, v21
	v_add_f32_e32 v11, v11, v12
	v_lshlrev_b32_e32 v12, 16, v154
	v_and_b32_e32 v13, 0xffff0000, v154
	v_lshlrev_b32_e32 v14, 16, v155
	v_and_b32_e32 v15, 0xffff0000, v155
	v_pk_mul_f32 v[8:9], v[8:9], v[20:21] op_sel_hi:[1,0]
	v_pk_mul_f32 v[6:7], v[6:7], v[20:21] op_sel_hi:[1,0]
	v_pk_fma_f32 v[8:9], v[132:133], v[8:9], v[14:15]
	v_pk_fma_f32 v[6:7], v[130:131], v[6:7], v[12:13]
	v_cndmask_b32_e32 v13, v9, v30, vcc
	v_cndmask_b32_e32 v15, v7, v30, vcc
	v_cndmask_b32_e32 v12, v8, v30, vcc
	v_cndmask_b32_e32 v14, v6, v30, vcc
	v_mul_f32_e32 v6, v15, v15
	v_mul_f32_e32 v7, v13, v13
	v_fmac_f32_e32 v6, v14, v14
	v_fmac_f32_e32 v7, v12, v12
	v_add_f32_e32 v11, v19, v11
	v_add_f32_e32 v6, v6, v7
	v_add_f32_e32 v11, v6, v11
	v_lshlrev_b32_e32 v6, 16, v152
	v_and_b32_e32 v7, 0xffff0000, v152
	v_lshlrev_b32_e32 v8, 16, v153
	v_and_b32_e32 v9, 0xffff0000, v153
	v_pk_mul_f32 v[4:5], v[4:5], v[20:21] op_sel_hi:[1,0]
	v_pk_mul_f32 v[2:3], v[2:3], v[20:21] op_sel_hi:[1,0]
	v_pk_fma_f32 v[4:5], v[128:129], v[4:5], v[8:9]
	v_pk_fma_f32 v[2:3], v[126:127], v[2:3], v[6:7]
	v_cndmask_b32_e32 v7, v5, v30, vcc
	v_cndmask_b32_e32 v9, v3, v30, vcc
	v_cndmask_b32_e32 v6, v4, v30, vcc
	v_cndmask_b32_e32 v8, v2, v30, vcc
	v_mul_f32_e32 v2, v9, v9
	v_mul_f32_e32 v3, v7, v7
	v_fmac_f32_e32 v2, v8, v8
	v_fmac_f32_e32 v3, v6, v6
	v_add_f32_e32 v2, v2, v3
	v_add_f32_e32 v2, v2, v11
	ds_bpermute_b32 v3, v1, v2
	v_cvt_pk_bf16_f32 v11, v21, v22
	v_mov_b32_e32 v242, v10
	v_mov_b32_e32 v243, v11
	s_nop 1
	v_permlane32_swap_b32_e32 v240, v242
	v_permlane32_swap_b32_e32 v241, v243
	s_nop 0
	v_permlane16_swap_b32_e32 v240, v242
	v_permlane16_swap_b32_e32 v241, v243
	v_lshl_add_u64 v[236:237], v[16:17], 0, v[238:239]
	global_store_dwordx4 v[236:237], v[240:243], off
	v_cvt_pk_bf16_f32 v4, v14, v15
	v_cvt_pk_bf16_f32 v5, v12, v13
	s_waitcnt lgkmcnt(0)
	v_add_f32_e32 v2, v2, v3
	ds_bpermute_b32 v3, v233, v2
	v_mov_b32_e32 v244, v4
	v_mov_b32_e32 v245, v5
	v_cvt_pk_bf16_f32 v4, v8, v9
	v_cvt_pk_bf16_f32 v5, v6, v7
	v_mov_b32_e32 v246, v4
	v_mov_b32_e32 v247, v5
	s_nop 1
	v_permlane32_swap_b32_e32 v244, v246
	v_permlane32_swap_b32_e32 v245, v247
	s_nop 0
	v_permlane16_swap_b32_e32 v244, v246
	v_permlane16_swap_b32_e32 v245, v247
	v_lshl_add_u64 v[236:237], v[16:17], 0, v[238:239]
	global_store_dwordx4 v[236:237], v[244:247], off offset:256
	s_and_saveexec_b64 s[0:1], s[4:5]
	s_cbranch_execz .LBB0_522
	v_lshl_add_u32 v4, v18, 4, s34
	s_waitcnt lgkmcnt(0)
	v_add_f32_e32 v2, v2, v3
	ds_write_b32 v4, v2 offset:16384
